# nt hint also on the late-transposed bf16 weight stores of phase 0 (consumed only from phase 6 on)
# baseline (speedup 1.0000x reference)
.LBB0_77:
	s_waitcnt lgkmcnt(0)
	ds_read2_b32 v[30:31], v48 offset1:33
	s_waitcnt lgkmcnt(0)
	v_cvt_pk_bf16_f32 v30, v30, v31
	ds_read2_b32 v[32:33], v48 offset0:66 offset1:99
	s_waitcnt lgkmcnt(0)
	v_cvt_pk_bf16_f32 v31, v32, v33
	ds_read2_b32 v[32:33], v48 offset0:132 offset1:165
	v_or_b32_e32 v36, v3, v47
	s_waitcnt lgkmcnt(0)
	v_cvt_pk_bf16_f32 v32, v32, v33
	ds_read2_b32 v[34:35], v48 offset0:198 offset1:231
	v_ashrrev_i32_e32 v29, 31, v28
	v_ashrrev_i32_e32 v37, 31, v36
	v_lshl_add_u64 v[38:39], v[28:29], 1, v[26:27]
	s_waitcnt lgkmcnt(0)
	v_cvt_pk_bf16_f32 v33, v34, v35
	v_lshlrev_b64 v[34:35], 11, v[36:37]
	v_lshl_add_u64 v[34:35], v[38:39], 0, v[34:35]
	global_store_dwordx4 v[34:35], v[30:33], off nt
	v_or_b32_e32 v34, v3, v49
	ds_read2_b32 v[28:29], v48 offset0:8 offset1:41
	v_ashrrev_i32_e32 v35, 31, v34
	s_waitcnt lgkmcnt(0)
	v_cvt_pk_bf16_f32 v28, v28, v29
	ds_read2_b32 v[30:31], v48 offset0:74 offset1:107
	v_lshlrev_b64 v[34:35], 11, v[34:35]
	s_waitcnt lgkmcnt(0)
	v_cvt_pk_bf16_f32 v29, v30, v31
	ds_read2_b32 v[30:31], v48 offset0:140 offset1:173
	v_lshl_add_u64 v[34:35], v[38:39], 0, v[34:35]
	s_waitcnt lgkmcnt(0)
	v_cvt_pk_bf16_f32 v30, v30, v31
	ds_read2_b32 v[32:33], v48 offset0:206 offset1:239
	s_waitcnt lgkmcnt(0)
	v_cvt_pk_bf16_f32 v31, v32, v33
	global_store_dwordx4 v[34:35], v[28:31], off nt
	v_or_b32_e32 v34, v3, v50
	ds_read2_b32 v[32:33], v48 offset0:16 offset1:49
	s_waitcnt lgkmcnt(0)
	v_cvt_pk_bf16_f32 v28, v32, v33
	ds_read2_b32 v[30:31], v48 offset0:82 offset1:115
	v_ashrrev_i32_e32 v35, 31, v34
	s_waitcnt lgkmcnt(0)
	v_cvt_pk_bf16_f32 v29, v30, v31
	ds_read2_b32 v[30:31], v48 offset0:148 offset1:181
	v_lshlrev_b64 v[34:35], 11, v[34:35]
	s_waitcnt lgkmcnt(0)
	v_cvt_pk_bf16_f32 v30, v30, v31
	ds_read2_b32 v[32:33], v48 offset0:214 offset1:247
	s_waitcnt lgkmcnt(0)
	v_cvt_pk_bf16_f32 v31, v32, v33
	v_lshl_add_u64 v[34:35], v[38:39], 0, v[34:35]
	ds_read2_b32 v[32:33], v48 offset0:24 offset1:57
	global_store_dwordx4 v[34:35], v[28:31], off nt
	v_or_b32_e32 v34, v3, v51
	v_ashrrev_i32_e32 v35, 31, v34
	s_waitcnt lgkmcnt(0)
	v_cvt_pk_bf16_f32 v28, v32, v33
	ds_read2_b32 v[30:31], v48 offset0:90 offset1:123
	s_waitcnt lgkmcnt(0)
	v_cvt_pk_bf16_f32 v29, v30, v31
	ds_read2_b32 v[30:31], v48 offset0:156 offset1:189
	s_waitcnt lgkmcnt(0)
	v_cvt_pk_bf16_f32 v30, v30, v31
	ds_read2_b32 v[32:33], v48 offset0:222 offset1:255
	v_lshlrev_b64 v[34:35], 11, v[34:35]
	s_waitcnt lgkmcnt(0)
	v_cvt_pk_bf16_f32 v31, v32, v33
	v_lshl_add_u64 v[32:33], v[38:39], 0, v[34:35]
	global_store_dwordx4 v[32:33], v[28:31], off nt
	s_waitcnt lgkmcnt(0)

.LBB0_89:
	s_lshl_b32 s43, s40, 1
	s_lshl_b32 s42, s39, 1
	v_or_b32_e32 v6, s43, v30
	s_add_i32 s45, s43, 4
	s_add_i32 s44, s42, 4
	s_add_i32 s46, s42, 8
	s_add_i32 s47, s43, 8
	v_lshlrev_b64 v[70:71], 12, v[6:7]
	v_or_b32_e32 v6, s45, v30
	v_mov_b32_e32 v35, v7
	v_mov_b32_e32 v37, v7
	v_mov_b32_e32 v39, v7
	v_or_b32_e32 v34, s42, v3
	s_add_i32 s48, s42, 12
	s_add_i32 s49, s43, 12
	s_add_i32 s50, s42, 16
	s_add_i32 s52, s42, 20
	s_add_i32 s54, s42, 24
	s_add_i32 s56, s42, 28
	v_or_b32_e32 v36, s44, v3
	v_or_b32_e32 v38, s46, v3
	v_lshlrev_b64 v[72:73], 12, v[6:7]
	v_or_b32_e32 v6, s47, v30
	v_mov_b32_e32 v41, v7
	v_mov_b32_e32 v43, v7
	v_mov_b32_e32 v45, v7
	v_mov_b32_e32 v67, v7
	v_mov_b32_e32 v69, v7
	s_add_i32 s51, s43, 16
	v_lshlrev_b64 v[34:35], 12, v[34:35]
	v_or_b32_e32 v40, s48, v3
	v_or_b32_e32 v42, s50, v3
	v_or_b32_e32 v44, s52, v3
	v_or_b32_e32 v66, s54, v3
	v_or_b32_e32 v68, s56, v3
	v_lshl_add_u64 v[70:71], v[28:29], 0, v[70:71]
	v_lshlrev_b64 v[36:37], 12, v[36:37]
	v_lshlrev_b64 v[38:39], 12, v[38:39]
	v_lshlrev_b64 v[74:75], 12, v[6:7]
	v_or_b32_e32 v6, s49, v30
	s_add_i32 s53, s43, 20
	v_lshl_add_u64 v[34:35], v[28:29], 0, v[34:35]
	v_lshlrev_b64 v[40:41], 12, v[40:41]
	v_lshlrev_b64 v[42:43], 12, v[42:43]
	v_lshlrev_b64 v[44:45], 12, v[44:45]
	v_lshlrev_b64 v[66:67], 12, v[66:67]
	v_lshlrev_b64 v[68:69], 12, v[68:69]
	v_lshl_add_u64 v[72:73], v[28:29], 0, v[72:73]
	v_lshl_add_u64 v[36:37], v[28:29], 0, v[36:37]
	v_lshl_add_u64 v[38:39], v[28:29], 0, v[38:39]
	global_load_dword v33, v[70:71], off nt
	global_load_dword v65, v[34:35], off nt
	v_lshlrev_b64 v[70:71], 12, v[6:7]
	v_or_b32_e32 v6, s51, v30
	s_add_i32 s55, s43, 24
	v_lshl_add_u64 v[40:41], v[28:29], 0, v[40:41]
	v_lshl_add_u64 v[42:43], v[28:29], 0, v[42:43]
	v_lshl_add_u64 v[44:45], v[28:29], 0, v[44:45]
	v_lshl_add_u64 v[66:67], v[28:29], 0, v[66:67]
	v_lshl_add_u64 v[68:69], v[28:29], 0, v[68:69]
	global_load_dword v86, v[72:73], off nt
	global_load_dword v87, v[36:37], off nt
	global_load_dword v88, v[38:39], off nt
	global_load_dword v89, v[40:41], off nt
	global_load_dword v90, v[42:43], off nt
	global_load_dword v91, v[44:45], off nt
	global_load_dword v92, v[66:67], off nt
	global_load_dword v93, v[68:69], off nt
	v_lshl_add_u64 v[36:37], v[28:29], 0, v[70:71]
	v_lshlrev_b64 v[38:39], 12, v[6:7]
	v_or_b32_e32 v6, s53, v30
	s_add_i32 s57, s43, 28
	v_lshl_add_u64 v[34:35], v[28:29], 0, v[74:75]
	global_load_dword v94, v[36:37], off nt
	global_load_dword v95, v[34:35], off nt
	v_lshlrev_b64 v[36:37], 12, v[6:7]
	v_or_b32_e32 v6, s55, v30
	v_lshl_add_u64 v[34:35], v[28:29], 0, v[38:39]
	v_lshlrev_b64 v[38:39], 12, v[6:7]
	v_or_b32_e32 v6, s57, v30
	v_lshlrev_b64 v[40:41], 12, v[6:7]
	v_lshl_add_u64 v[40:41], v[28:29], 0, v[40:41]
	v_lshl_add_u64 v[36:37], v[28:29], 0, v[36:37]
	v_lshl_add_u64 v[38:39], v[28:29], 0, v[38:39]
	global_load_dword v6, v[40:41], off nt
	global_load_dword v96, v[38:39], off nt
	global_load_dword v97, v[36:37], off nt
	global_load_dword v98, v[34:35], off nt
	v_or_b32_e32 v36, s42, v1
	v_or_b32_e32 v34, s43, v2
	s_add_i32 s40, s40, 16
	s_add_i32 s39, s39, 16
	s_add_i32 s41, s41, -16
	v_mad_u64_u32 v[34:35], s[42:43], v34, s25, v[4:5]
	v_mad_u64_u32 v[36:37], s[42:43], v36, s25, v[4:5]
	v_or_b32_e32 v35, s44, v1
	v_or_b32_e32 v37, s45, v2
	v_or_b32_e32 v44, s46, v1
	v_or_b32_e32 v42, s47, v2
	v_or_b32_e32 v68, s48, v1
	v_or_b32_e32 v66, s49, v2
	v_or_b32_e32 v72, s50, v1
	v_or_b32_e32 v70, s51, v2
	v_or_b32_e32 v76, s52, v1
	v_or_b32_e32 v74, s53, v2
	v_or_b32_e32 v80, s54, v1
	v_or_b32_e32 v78, s55, v2
	v_or_b32_e32 v84, s56, v1
	v_or_b32_e32 v82, s57, v2
	s_cmp_lg_u32 s41, 0
	v_mad_u64_u32 v[38:39], s[42:43], v37, s25, v[4:5]
	v_mad_u64_u32 v[40:41], s[42:43], v35, s25, v[4:5]
	v_mad_u64_u32 v[42:43], s[42:43], v42, s25, v[4:5]
	v_mad_u64_u32 v[44:45], s[42:43], v44, s25, v[4:5]
	v_mad_u64_u32 v[66:67], s[42:43], v66, s25, v[4:5]
	v_mad_u64_u32 v[68:69], s[42:43], v68, s25, v[4:5]
	v_mad_u64_u32 v[70:71], s[42:43], v70, s25, v[4:5]
	v_mad_u64_u32 v[72:73], s[42:43], v72, s25, v[4:5]
	v_mad_u64_u32 v[74:75], s[42:43], v74, s25, v[4:5]
	v_mad_u64_u32 v[76:77], s[42:43], v76, s25, v[4:5]
	v_mad_u64_u32 v[78:79], s[42:43], v78, s25, v[4:5]
	v_mad_u64_u32 v[80:81], s[42:43], v80, s25, v[4:5]
	v_mad_u64_u32 v[82:83], s[42:43], v82, s25, v[4:5]
	v_mad_u64_u32 v[84:85], s[42:43], v84, s25, v[4:5]
	s_waitcnt vmcnt(15)
	ds_write_b32 v34, v33
	s_waitcnt vmcnt(14)
	ds_write_b32 v36, v65
	s_waitcnt vmcnt(13)
	ds_write_b32 v38, v86
	s_waitcnt vmcnt(12)
	ds_write_b32 v40, v87
	s_waitcnt vmcnt(4)
	ds_write_b32 v42, v95
	ds_write_b32 v44, v88
	ds_write_b32 v66, v94
	ds_write_b32 v68, v89
	s_waitcnt vmcnt(0)
	ds_write_b32 v70, v98
	ds_write_b32 v72, v90
	ds_write_b32 v74, v97
	ds_write_b32 v76, v91
	ds_write_b32 v78, v96
	ds_write_b32 v80, v92
	ds_write_b32 v82, v6
	ds_write_b32 v84, v93
	s_cbranch_scc1 .LBB0_89
	s_waitcnt lgkmcnt(0)
	ds_read2_b32 v[28:29], v48 offset1:33
	s_waitcnt lgkmcnt(0)
	v_cvt_pk_bf16_f32 v34, v28, v29
	ds_read2_b32 v[28:29], v48 offset0:66 offset1:99
	s_waitcnt lgkmcnt(0)
	v_cvt_pk_bf16_f32 v35, v28, v29
	ds_read2_b32 v[28:29], v48 offset0:132 offset1:165
	v_lshlrev_b32_e32 v6, 1, v32
	v_or_b32_e32 v3, v31, v47
	s_waitcnt lgkmcnt(0)
	v_cvt_pk_bf16_f32 v36, v28, v29
	ds_read2_b32 v[28:29], v48 offset0:198 offset1:231
	v_lshl_add_u64 v[38:39], v[8:9], 0, v[6:7]
	v_lshlrev_b32_e32 v6, 12, v3
	s_waitcnt lgkmcnt(0)
	v_cvt_pk_bf16_f32 v37, v28, v29
	ds_read2_b32 v[28:29], v48 offset0:8 offset1:41
	v_lshl_add_u64 v[32:33], v[38:39], 0, v[6:7]
	global_store_dwordx4 v[32:33], v[34:37], off nt
	s_waitcnt lgkmcnt(0)
	v_cvt_pk_bf16_f32 v32, v28, v29
	ds_read2_b32 v[28:29], v48 offset0:74 offset1:107
	s_waitcnt lgkmcnt(0)
	v_cvt_pk_bf16_f32 v33, v28, v29
	ds_read2_b32 v[28:29], v48 offset0:140 offset1:173
	v_or_b32_e32 v3, v31, v49
	s_waitcnt lgkmcnt(0)
	v_cvt_pk_bf16_f32 v34, v28, v29
	ds_read2_b32 v[28:29], v48 offset0:206 offset1:239
	v_lshlrev_b32_e32 v6, 12, v3
	s_waitcnt lgkmcnt(0)
	v_cvt_pk_bf16_f32 v35, v28, v29
	ds_read2_b32 v[28:29], v48 offset0:16 offset1:49
	v_lshl_add_u64 v[36:37], v[38:39], 0, v[6:7]
	global_store_dwordx4 v[36:37], v[32:35], off nt
	v_or_b32_e32 v3, v31, v50
	v_lshlrev_b32_e32 v6, 12, v3
	s_waitcnt lgkmcnt(0)
	v_cvt_pk_bf16_f32 v32, v28, v29
	ds_read2_b32 v[28:29], v48 offset0:82 offset1:115
	s_waitcnt lgkmcnt(0)
	v_cvt_pk_bf16_f32 v33, v28, v29
	ds_read2_b32 v[28:29], v48 offset0:148 offset1:181
	s_waitcnt lgkmcnt(0)
	v_cvt_pk_bf16_f32 v34, v28, v29
	ds_read2_b32 v[28:29], v48 offset0:214 offset1:247
	s_waitcnt lgkmcnt(0)
	v_cvt_pk_bf16_f32 v35, v28, v29
	ds_read2_b32 v[28:29], v48 offset0:24 offset1:57
	v_lshl_add_u64 v[36:37], v[38:39], 0, v[6:7]
	global_store_dwordx4 v[36:37], v[32:35], off nt
	s_waitcnt lgkmcnt(0)
	v_cvt_pk_bf16_f32 v28, v28, v29
	ds_read2_b32 v[32:33], v48 offset0:90 offset1:123
	s_waitcnt lgkmcnt(0)
	v_cvt_pk_bf16_f32 v29, v32, v33
	ds_read2_b32 v[32:33], v48 offset0:156 offset1:189
	v_or_b32_e32 v3, v31, v51
	s_waitcnt lgkmcnt(0)
	v_cvt_pk_bf16_f32 v30, v32, v33
	ds_read2_b32 v[32:33], v48 offset0:222 offset1:255
	v_lshlrev_b32_e32 v6, 12, v3
	s_waitcnt lgkmcnt(0)
	v_cvt_pk_bf16_f32 v31, v32, v33
	v_lshl_add_u64 v[32:33], v[38:39], 0, v[6:7]
	global_store_dwordx4 v[32:33], v[28:31], off nt
	s_waitcnt lgkmcnt(0)

.LBB0_93:
	s_lshl_b32 s43, s40, 1
	s_lshl_b32 s42, s39, 1
	v_or_b32_e32 v6, s43, v30
	s_add_i32 s45, s43, 4
	s_add_i32 s44, s42, 4
	s_add_i32 s46, s42, 8
	s_add_i32 s47, s43, 8
	v_lshlrev_b64 v[70:71], 12, v[6:7]
	v_or_b32_e32 v6, s45, v30
	v_mov_b32_e32 v35, v7
	v_mov_b32_e32 v37, v7
	v_mov_b32_e32 v39, v7
	v_or_b32_e32 v34, s42, v3
	s_add_i32 s48, s42, 12
	s_add_i32 s49, s43, 12
	s_add_i32 s50, s42, 16
	s_add_i32 s52, s42, 20
	s_add_i32 s54, s42, 24
	s_add_i32 s56, s42, 28
	v_or_b32_e32 v36, s44, v3
	v_or_b32_e32 v38, s46, v3
	v_lshlrev_b64 v[72:73], 12, v[6:7]
	v_or_b32_e32 v6, s47, v30
	v_mov_b32_e32 v41, v7
	v_mov_b32_e32 v43, v7
	v_mov_b32_e32 v45, v7
	v_mov_b32_e32 v67, v7
	v_mov_b32_e32 v69, v7
	s_add_i32 s51, s43, 16
	v_lshlrev_b64 v[34:35], 12, v[34:35]
	v_or_b32_e32 v40, s48, v3
	v_or_b32_e32 v42, s50, v3
	v_or_b32_e32 v44, s52, v3
	v_or_b32_e32 v66, s54, v3
	v_or_b32_e32 v68, s56, v3
	v_lshl_add_u64 v[70:71], v[28:29], 0, v[70:71]
	v_lshlrev_b64 v[36:37], 12, v[36:37]
	v_lshlrev_b64 v[38:39], 12, v[38:39]
	v_lshlrev_b64 v[74:75], 12, v[6:7]
	v_or_b32_e32 v6, s49, v30
	s_add_i32 s53, s43, 20
	v_lshl_add_u64 v[34:35], v[28:29], 0, v[34:35]
	v_lshlrev_b64 v[40:41], 12, v[40:41]
	v_lshlrev_b64 v[42:43], 12, v[42:43]
	v_lshlrev_b64 v[44:45], 12, v[44:45]
	v_lshlrev_b64 v[66:67], 12, v[66:67]
	v_lshlrev_b64 v[68:69], 12, v[68:69]
	v_lshl_add_u64 v[72:73], v[28:29], 0, v[72:73]
	v_lshl_add_u64 v[36:37], v[28:29], 0, v[36:37]
	v_lshl_add_u64 v[38:39], v[28:29], 0, v[38:39]
	global_load_dword v33, v[70:71], off nt
	global_load_dword v65, v[34:35], off nt
	v_lshlrev_b64 v[70:71], 12, v[6:7]
	v_or_b32_e32 v6, s51, v30
	s_add_i32 s55, s43, 24
	v_lshl_add_u64 v[40:41], v[28:29], 0, v[40:41]
	v_lshl_add_u64 v[42:43], v[28:29], 0, v[42:43]
	v_lshl_add_u64 v[44:45], v[28:29], 0, v[44:45]
	v_lshl_add_u64 v[66:67], v[28:29], 0, v[66:67]
	v_lshl_add_u64 v[68:69], v[28:29], 0, v[68:69]
	global_load_dword v86, v[72:73], off nt
	global_load_dword v87, v[36:37], off nt
	global_load_dword v88, v[38:39], off nt
	global_load_dword v89, v[40:41], off nt
	global_load_dword v90, v[42:43], off nt
	global_load_dword v91, v[44:45], off nt
	global_load_dword v92, v[66:67], off nt
	global_load_dword v93, v[68:69], off nt
	v_lshl_add_u64 v[36:37], v[28:29], 0, v[70:71]
	v_lshlrev_b64 v[38:39], 12, v[6:7]
	v_or_b32_e32 v6, s53, v30
	s_add_i32 s57, s43, 28
	v_lshl_add_u64 v[34:35], v[28:29], 0, v[74:75]
	global_load_dword v94, v[36:37], off nt
	global_load_dword v95, v[34:35], off nt
	v_lshlrev_b64 v[36:37], 12, v[6:7]
	v_or_b32_e32 v6, s55, v30
	v_lshl_add_u64 v[34:35], v[28:29], 0, v[38:39]
	v_lshlrev_b64 v[38:39], 12, v[6:7]
	v_or_b32_e32 v6, s57, v30
	v_lshlrev_b64 v[40:41], 12, v[6:7]
	v_lshl_add_u64 v[40:41], v[28:29], 0, v[40:41]
	v_lshl_add_u64 v[36:37], v[28:29], 0, v[36:37]
	v_lshl_add_u64 v[38:39], v[28:29], 0, v[38:39]
	global_load_dword v6, v[40:41], off nt
	global_load_dword v96, v[38:39], off nt
	global_load_dword v97, v[36:37], off nt
	global_load_dword v98, v[34:35], off nt
	v_or_b32_e32 v36, s42, v1
	v_or_b32_e32 v34, s43, v2
	s_add_i32 s40, s40, 16
	s_add_i32 s39, s39, 16
	s_add_i32 s41, s41, -16
	v_mad_u64_u32 v[34:35], s[42:43], v34, s25, v[4:5]
	v_mad_u64_u32 v[36:37], s[42:43], v36, s25, v[4:5]
	v_or_b32_e32 v35, s44, v1
	v_or_b32_e32 v37, s45, v2
	v_or_b32_e32 v44, s46, v1
	v_or_b32_e32 v42, s47, v2
	v_or_b32_e32 v68, s48, v1
	v_or_b32_e32 v66, s49, v2
	v_or_b32_e32 v72, s50, v1
	v_or_b32_e32 v70, s51, v2
	v_or_b32_e32 v76, s52, v1
	v_or_b32_e32 v74, s53, v2
	v_or_b32_e32 v80, s54, v1
	v_or_b32_e32 v78, s55, v2
	v_or_b32_e32 v84, s56, v1
	v_or_b32_e32 v82, s57, v2
	s_cmp_lg_u32 s41, 0
	v_mad_u64_u32 v[38:39], s[42:43], v37, s25, v[4:5]
	v_mad_u64_u32 v[40:41], s[42:43], v35, s25, v[4:5]
	v_mad_u64_u32 v[42:43], s[42:43], v42, s25, v[4:5]
	v_mad_u64_u32 v[44:45], s[42:43], v44, s25, v[4:5]
	v_mad_u64_u32 v[66:67], s[42:43], v66, s25, v[4:5]
	v_mad_u64_u32 v[68:69], s[42:43], v68, s25, v[4:5]
	v_mad_u64_u32 v[70:71], s[42:43], v70, s25, v[4:5]
	v_mad_u64_u32 v[72:73], s[42:43], v72, s25, v[4:5]
	v_mad_u64_u32 v[74:75], s[42:43], v74, s25, v[4:5]
	v_mad_u64_u32 v[76:77], s[42:43], v76, s25, v[4:5]
	v_mad_u64_u32 v[78:79], s[42:43], v78, s25, v[4:5]
	v_mad_u64_u32 v[80:81], s[42:43], v80, s25, v[4:5]
	v_mad_u64_u32 v[82:83], s[42:43], v82, s25, v[4:5]
	v_mad_u64_u32 v[84:85], s[42:43], v84, s25, v[4:5]
	s_waitcnt vmcnt(15)
	ds_write_b32 v34, v33
	s_waitcnt vmcnt(14)
	ds_write_b32 v36, v65
	s_waitcnt vmcnt(13)
	ds_write_b32 v38, v86
	s_waitcnt vmcnt(12)
	ds_write_b32 v40, v87
	s_waitcnt vmcnt(4)
	ds_write_b32 v42, v95
	ds_write_b32 v44, v88
	ds_write_b32 v66, v94
	ds_write_b32 v68, v89
	s_waitcnt vmcnt(0)
	ds_write_b32 v70, v98
	ds_write_b32 v72, v90
	ds_write_b32 v74, v97
	ds_write_b32 v76, v91
	ds_write_b32 v78, v96
	ds_write_b32 v80, v92
	ds_write_b32 v82, v6
	ds_write_b32 v84, v93
	s_cbranch_scc1 .LBB0_93
	s_waitcnt lgkmcnt(0)
	ds_read2_b32 v[28:29], v48 offset1:33
	s_waitcnt lgkmcnt(0)
	v_cvt_pk_bf16_f32 v34, v28, v29
	ds_read2_b32 v[28:29], v48 offset0:66 offset1:99
	s_waitcnt lgkmcnt(0)
	v_cvt_pk_bf16_f32 v35, v28, v29
	ds_read2_b32 v[28:29], v48 offset0:132 offset1:165
	v_lshlrev_b32_e32 v6, 1, v32
	v_or_b32_e32 v3, v31, v47
	s_waitcnt lgkmcnt(0)
	v_cvt_pk_bf16_f32 v36, v28, v29
	ds_read2_b32 v[28:29], v48 offset0:198 offset1:231
	v_lshl_add_u64 v[38:39], v[10:11], 0, v[6:7]
	v_lshlrev_b32_e32 v6, 12, v3
	s_waitcnt lgkmcnt(0)
	v_cvt_pk_bf16_f32 v37, v28, v29
	ds_read2_b32 v[28:29], v48 offset0:8 offset1:41
	v_lshl_add_u64 v[32:33], v[38:39], 0, v[6:7]
	global_store_dwordx4 v[32:33], v[34:37], off nt
	s_waitcnt lgkmcnt(0)
	v_cvt_pk_bf16_f32 v32, v28, v29
	ds_read2_b32 v[28:29], v48 offset0:74 offset1:107
	s_waitcnt lgkmcnt(0)
	v_cvt_pk_bf16_f32 v33, v28, v29
	ds_read2_b32 v[28:29], v48 offset0:140 offset1:173
	v_or_b32_e32 v3, v31, v49
	s_waitcnt lgkmcnt(0)
	v_cvt_pk_bf16_f32 v34, v28, v29
	ds_read2_b32 v[28:29], v48 offset0:206 offset1:239
	v_lshlrev_b32_e32 v6, 12, v3
	s_waitcnt lgkmcnt(0)
	v_cvt_pk_bf16_f32 v35, v28, v29
	ds_read2_b32 v[28:29], v48 offset0:16 offset1:49
	v_lshl_add_u64 v[36:37], v[38:39], 0, v[6:7]
	global_store_dwordx4 v[36:37], v[32:35], off nt
	v_or_b32_e32 v3, v31, v50
	v_lshlrev_b32_e32 v6, 12, v3
	s_waitcnt lgkmcnt(0)
	v_cvt_pk_bf16_f32 v32, v28, v29
	ds_read2_b32 v[28:29], v48 offset0:82 offset1:115
	s_waitcnt lgkmcnt(0)
	v_cvt_pk_bf16_f32 v33, v28, v29
	ds_read2_b32 v[28:29], v48 offset0:148 offset1:181
	s_waitcnt lgkmcnt(0)
	v_cvt_pk_bf16_f32 v34, v28, v29
	ds_read2_b32 v[28:29], v48 offset0:214 offset1:247
	s_waitcnt lgkmcnt(0)
	v_cvt_pk_bf16_f32 v35, v28, v29
	ds_read2_b32 v[28:29], v48 offset0:24 offset1:57
	v_lshl_add_u64 v[36:37], v[38:39], 0, v[6:7]
	global_store_dwordx4 v[36:37], v[32:35], off nt
	s_waitcnt lgkmcnt(0)
	v_cvt_pk_bf16_f32 v28, v28, v29
	ds_read2_b32 v[32:33], v48 offset0:90 offset1:123
	s_waitcnt lgkmcnt(0)
	v_cvt_pk_bf16_f32 v29, v32, v33
	ds_read2_b32 v[32:33], v48 offset0:156 offset1:189
	v_or_b32_e32 v3, v31, v51
	s_waitcnt lgkmcnt(0)
	v_cvt_pk_bf16_f32 v30, v32, v33
	ds_read2_b32 v[32:33], v48 offset0:222 offset1:255
	v_lshlrev_b32_e32 v6, 12, v3
	s_waitcnt lgkmcnt(0)
	v_cvt_pk_bf16_f32 v31, v32, v33
	v_lshl_add_u64 v[32:33], v[38:39], 0, v[6:7]
	global_store_dwordx4 v[32:33], v[28:31], off nt
	s_waitcnt lgkmcnt(0)

.LBB0_98:
	s_lshl_b32 s41, s27, 1
	s_lshl_b32 s40, s26, 1
	v_or_b32_e32 v6, s41, v30
	s_add_i32 s43, s41, 4
	s_add_i32 s42, s40, 4
	s_add_i32 s44, s40, 8
	s_add_i32 s45, s41, 8
	v_lshlrev_b64 v[70:71], 14, v[6:7]
	v_or_b32_e32 v6, s43, v30
	v_mov_b32_e32 v35, v7
	v_mov_b32_e32 v37, v7
	v_mov_b32_e32 v39, v7
	v_or_b32_e32 v34, s40, v3
	s_add_i32 s46, s40, 12
	s_add_i32 s47, s41, 12
	s_add_i32 s48, s40, 16
	s_add_i32 s50, s40, 20
	s_add_i32 s52, s40, 24
	s_add_i32 s54, s40, 28
	v_or_b32_e32 v36, s42, v3
	v_or_b32_e32 v38, s44, v3
	v_lshlrev_b64 v[72:73], 14, v[6:7]
	v_or_b32_e32 v6, s45, v30
	v_mov_b32_e32 v41, v7
	v_mov_b32_e32 v43, v7
	v_mov_b32_e32 v45, v7
	v_mov_b32_e32 v67, v7
	v_mov_b32_e32 v69, v7
	s_add_i32 s49, s41, 16
	v_lshlrev_b64 v[34:35], 14, v[34:35]
	v_or_b32_e32 v40, s46, v3
	v_or_b32_e32 v42, s48, v3
	v_or_b32_e32 v44, s50, v3
	v_or_b32_e32 v66, s52, v3
	v_or_b32_e32 v68, s54, v3
	v_lshl_add_u64 v[70:71], v[28:29], 0, v[70:71]
	v_lshlrev_b64 v[36:37], 14, v[36:37]
	v_lshlrev_b64 v[38:39], 14, v[38:39]
	v_lshlrev_b64 v[74:75], 14, v[6:7]
	v_or_b32_e32 v6, s47, v30
	s_add_i32 s51, s41, 20
	v_lshl_add_u64 v[34:35], v[28:29], 0, v[34:35]
	v_lshlrev_b64 v[40:41], 14, v[40:41]
	v_lshlrev_b64 v[42:43], 14, v[42:43]
	v_lshlrev_b64 v[44:45], 14, v[44:45]
	v_lshlrev_b64 v[66:67], 14, v[66:67]
	v_lshlrev_b64 v[68:69], 14, v[68:69]
	v_lshl_add_u64 v[72:73], v[28:29], 0, v[72:73]
	v_lshl_add_u64 v[36:37], v[28:29], 0, v[36:37]
	v_lshl_add_u64 v[38:39], v[28:29], 0, v[38:39]
	global_load_dword v33, v[70:71], off nt
	global_load_dword v65, v[34:35], off nt
	v_lshlrev_b64 v[70:71], 14, v[6:7]
	v_or_b32_e32 v6, s49, v30
	s_add_i32 s53, s41, 24
	v_lshl_add_u64 v[40:41], v[28:29], 0, v[40:41]
	v_lshl_add_u64 v[42:43], v[28:29], 0, v[42:43]
	v_lshl_add_u64 v[44:45], v[28:29], 0, v[44:45]
	v_lshl_add_u64 v[66:67], v[28:29], 0, v[66:67]
	v_lshl_add_u64 v[68:69], v[28:29], 0, v[68:69]
	global_load_dword v86, v[72:73], off nt
	global_load_dword v87, v[36:37], off nt
	global_load_dword v88, v[38:39], off nt
	global_load_dword v89, v[40:41], off nt
	global_load_dword v90, v[42:43], off nt
	global_load_dword v91, v[44:45], off nt
	global_load_dword v92, v[66:67], off nt
	global_load_dword v93, v[68:69], off nt
	v_lshl_add_u64 v[36:37], v[28:29], 0, v[70:71]
	v_lshlrev_b64 v[38:39], 14, v[6:7]
	v_or_b32_e32 v6, s51, v30
	s_add_i32 s55, s41, 28
	v_lshl_add_u64 v[34:35], v[28:29], 0, v[74:75]
	global_load_dword v94, v[36:37], off nt
	global_load_dword v95, v[34:35], off nt
	v_lshlrev_b64 v[36:37], 14, v[6:7]
	v_or_b32_e32 v6, s53, v30
	v_lshl_add_u64 v[34:35], v[28:29], 0, v[38:39]
	v_lshlrev_b64 v[38:39], 14, v[6:7]
	v_or_b32_e32 v6, s55, v30
	v_lshlrev_b64 v[40:41], 14, v[6:7]
	v_lshl_add_u64 v[40:41], v[28:29], 0, v[40:41]
	v_lshl_add_u64 v[36:37], v[28:29], 0, v[36:37]
	v_lshl_add_u64 v[38:39], v[28:29], 0, v[38:39]
	global_load_dword v6, v[40:41], off nt
	global_load_dword v96, v[38:39], off nt
	global_load_dword v97, v[36:37], off nt
	global_load_dword v98, v[34:35], off nt
	v_or_b32_e32 v36, s40, v1
	v_or_b32_e32 v34, s41, v2
	s_add_i32 s27, s27, 16
	s_add_i32 s26, s26, 16
	s_add_i32 s39, s39, -16
	v_mad_u64_u32 v[34:35], s[40:41], v34, s25, v[4:5]
	v_mad_u64_u32 v[36:37], s[40:41], v36, s25, v[4:5]
	v_or_b32_e32 v35, s42, v1
	v_or_b32_e32 v37, s43, v2
	v_or_b32_e32 v44, s44, v1
	v_or_b32_e32 v42, s45, v2
	v_or_b32_e32 v68, s46, v1
	v_or_b32_e32 v66, s47, v2
	v_or_b32_e32 v72, s48, v1
	v_or_b32_e32 v70, s49, v2
	v_or_b32_e32 v76, s50, v1
	v_or_b32_e32 v74, s51, v2
	v_or_b32_e32 v80, s52, v1
	v_or_b32_e32 v78, s53, v2
	v_or_b32_e32 v84, s54, v1
	v_or_b32_e32 v82, s55, v2
	s_cmp_lg_u32 s39, 0
	v_mad_u64_u32 v[38:39], s[40:41], v37, s25, v[4:5]
	v_mad_u64_u32 v[40:41], s[40:41], v35, s25, v[4:5]
	v_mad_u64_u32 v[42:43], s[40:41], v42, s25, v[4:5]
	v_mad_u64_u32 v[44:45], s[40:41], v44, s25, v[4:5]
	v_mad_u64_u32 v[66:67], s[40:41], v66, s25, v[4:5]
	v_mad_u64_u32 v[68:69], s[40:41], v68, s25, v[4:5]
	v_mad_u64_u32 v[70:71], s[40:41], v70, s25, v[4:5]
	v_mad_u64_u32 v[72:73], s[40:41], v72, s25, v[4:5]
	v_mad_u64_u32 v[74:75], s[40:41], v74, s25, v[4:5]
	v_mad_u64_u32 v[76:77], s[40:41], v76, s25, v[4:5]
	v_mad_u64_u32 v[78:79], s[40:41], v78, s25, v[4:5]
	v_mad_u64_u32 v[80:81], s[40:41], v80, s25, v[4:5]
	v_mad_u64_u32 v[82:83], s[40:41], v82, s25, v[4:5]
	v_mad_u64_u32 v[84:85], s[40:41], v84, s25, v[4:5]
	s_waitcnt vmcnt(15)
	ds_write_b32 v34, v33
	s_waitcnt vmcnt(14)
	ds_write_b32 v36, v65
	s_waitcnt vmcnt(13)
	ds_write_b32 v38, v86
	s_waitcnt vmcnt(12)
	ds_write_b32 v40, v87
	s_waitcnt vmcnt(4)
	ds_write_b32 v42, v95
	ds_write_b32 v44, v88
	ds_write_b32 v66, v94
	ds_write_b32 v68, v89
	s_waitcnt vmcnt(0)
	ds_write_b32 v70, v98
	ds_write_b32 v72, v90
	ds_write_b32 v74, v97
	ds_write_b32 v76, v91
	ds_write_b32 v78, v96
	ds_write_b32 v80, v92
	ds_write_b32 v82, v6
	ds_write_b32 v84, v93
	s_cbranch_scc1 .LBB0_98
	s_waitcnt lgkmcnt(0)
	ds_read2_b32 v[28:29], v48 offset1:33
	s_waitcnt lgkmcnt(0)
	v_cvt_pk_bf16_f32 v34, v28, v29
	ds_read2_b32 v[28:29], v48 offset0:66 offset1:99
	s_waitcnt lgkmcnt(0)
	v_cvt_pk_bf16_f32 v35, v28, v29
	ds_read2_b32 v[28:29], v48 offset0:132 offset1:165
	v_lshlrev_b32_e32 v6, 1, v32
	v_or_b32_e32 v3, v31, v47
	s_waitcnt lgkmcnt(0)
	v_cvt_pk_bf16_f32 v36, v28, v29
	ds_read2_b32 v[28:29], v48 offset0:198 offset1:231
	v_lshl_add_u64 v[38:39], v[12:13], 0, v[6:7]
	v_lshlrev_b32_e32 v6, 11, v3
	s_waitcnt lgkmcnt(0)
	v_cvt_pk_bf16_f32 v37, v28, v29
	ds_read2_b32 v[28:29], v48 offset0:8 offset1:41
	v_lshl_add_u64 v[32:33], v[38:39], 0, v[6:7]
	global_store_dwordx4 v[32:33], v[34:37], off nt
	s_waitcnt lgkmcnt(0)
	v_cvt_pk_bf16_f32 v32, v28, v29
	ds_read2_b32 v[28:29], v48 offset0:74 offset1:107
	s_waitcnt lgkmcnt(0)
	v_cvt_pk_bf16_f32 v33, v28, v29
	ds_read2_b32 v[28:29], v48 offset0:140 offset1:173
	v_or_b32_e32 v3, v31, v49
	s_waitcnt lgkmcnt(0)
	v_cvt_pk_bf16_f32 v34, v28, v29
	ds_read2_b32 v[28:29], v48 offset0:206 offset1:239
	v_lshlrev_b32_e32 v6, 11, v3
	s_waitcnt lgkmcnt(0)
	v_cvt_pk_bf16_f32 v35, v28, v29
	ds_read2_b32 v[28:29], v48 offset0:16 offset1:49
	v_lshl_add_u64 v[36:37], v[38:39], 0, v[6:7]
	global_store_dwordx4 v[36:37], v[32:35], off nt
	v_or_b32_e32 v3, v31, v50
	v_lshlrev_b32_e32 v6, 11, v3
	s_waitcnt lgkmcnt(0)
	v_cvt_pk_bf16_f32 v32, v28, v29
	ds_read2_b32 v[28:29], v48 offset0:82 offset1:115
	s_waitcnt lgkmcnt(0)
	v_cvt_pk_bf16_f32 v33, v28, v29
	ds_read2_b32 v[28:29], v48 offset0:148 offset1:181
	s_waitcnt lgkmcnt(0)
	v_cvt_pk_bf16_f32 v34, v28, v29
	ds_read2_b32 v[28:29], v48 offset0:214 offset1:247
	s_waitcnt lgkmcnt(0)
	v_cvt_pk_bf16_f32 v35, v28, v29
	ds_read2_b32 v[28:29], v48 offset0:24 offset1:57
	v_lshl_add_u64 v[36:37], v[38:39], 0, v[6:7]
	global_store_dwordx4 v[36:37], v[32:35], off nt
	s_waitcnt lgkmcnt(0)
	v_cvt_pk_bf16_f32 v28, v28, v29
	ds_read2_b32 v[32:33], v48 offset0:90 offset1:123
	s_waitcnt lgkmcnt(0)
	v_cvt_pk_bf16_f32 v29, v32, v33
	ds_read2_b32 v[32:33], v48 offset0:156 offset1:189
	v_or_b32_e32 v3, v31, v51
	s_waitcnt lgkmcnt(0)
	v_cvt_pk_bf16_f32 v30, v32, v33
	ds_read2_b32 v[32:33], v48 offset0:222 offset1:255
	v_lshlrev_b32_e32 v6, 11, v3
	s_waitcnt lgkmcnt(0)
	v_cvt_pk_bf16_f32 v31, v32, v33
	v_lshl_add_u64 v[32:33], v[38:39], 0, v[6:7]
	global_store_dwordx4 v[32:33], v[28:31], off nt
	s_waitcnt lgkmcnt(0)

.LBB0_103:
	s_lshl_b32 s39, s23, 1
	s_lshl_b32 s27, s22, 1
	v_or_b32_e32 v6, s39, v30
	s_add_i32 s43, s39, 4
	s_add_i32 s42, s27, 4
	s_add_i32 s44, s27, 8
	s_add_i32 s45, s39, 8
	v_lshlrev_b64 v[70:71], 12, v[6:7]
	v_or_b32_e32 v6, s43, v30
	v_mov_b32_e32 v35, v7
	v_mov_b32_e32 v37, v7
	v_mov_b32_e32 v39, v7
	v_or_b32_e32 v34, s27, v3
	s_add_i32 s46, s27, 12
	s_add_i32 s47, s39, 12
	s_add_i32 s48, s27, 16
	s_add_i32 s50, s27, 20
	s_add_i32 s52, s27, 24
	s_add_i32 s54, s27, 28
	v_or_b32_e32 v36, s42, v3
	v_or_b32_e32 v38, s44, v3
	v_lshlrev_b64 v[72:73], 12, v[6:7]
	v_or_b32_e32 v6, s45, v30
	v_mov_b32_e32 v41, v7
	v_mov_b32_e32 v43, v7
	v_mov_b32_e32 v45, v7
	v_mov_b32_e32 v67, v7
	v_mov_b32_e32 v69, v7
	s_add_i32 s49, s39, 16
	v_lshlrev_b64 v[34:35], 12, v[34:35]
	v_or_b32_e32 v40, s46, v3
	v_or_b32_e32 v42, s48, v3
	v_or_b32_e32 v44, s50, v3
	v_or_b32_e32 v66, s52, v3
	v_or_b32_e32 v68, s54, v3
	v_lshl_add_u64 v[70:71], v[28:29], 0, v[70:71]
	v_lshlrev_b64 v[36:37], 12, v[36:37]
	v_lshlrev_b64 v[38:39], 12, v[38:39]
	v_lshlrev_b64 v[74:75], 12, v[6:7]
	v_or_b32_e32 v6, s47, v30
	s_add_i32 s51, s39, 20
	v_lshl_add_u64 v[34:35], v[28:29], 0, v[34:35]
	v_lshlrev_b64 v[40:41], 12, v[40:41]
	v_lshlrev_b64 v[42:43], 12, v[42:43]
	v_lshlrev_b64 v[44:45], 12, v[44:45]
	v_lshlrev_b64 v[66:67], 12, v[66:67]
	v_lshlrev_b64 v[68:69], 12, v[68:69]
	v_lshl_add_u64 v[72:73], v[28:29], 0, v[72:73]
	v_lshl_add_u64 v[36:37], v[28:29], 0, v[36:37]
	v_lshl_add_u64 v[38:39], v[28:29], 0, v[38:39]
	global_load_dword v33, v[70:71], off nt
	global_load_dword v65, v[34:35], off nt
	v_lshlrev_b64 v[70:71], 12, v[6:7]
	v_or_b32_e32 v6, s49, v30
	s_add_i32 s53, s39, 24
	v_lshl_add_u64 v[40:41], v[28:29], 0, v[40:41]
	v_lshl_add_u64 v[42:43], v[28:29], 0, v[42:43]
	v_lshl_add_u64 v[44:45], v[28:29], 0, v[44:45]
	v_lshl_add_u64 v[66:67], v[28:29], 0, v[66:67]
	v_lshl_add_u64 v[68:69], v[28:29], 0, v[68:69]
	global_load_dword v86, v[72:73], off nt
	global_load_dword v87, v[36:37], off nt
	global_load_dword v88, v[38:39], off nt
	global_load_dword v89, v[40:41], off nt
	global_load_dword v90, v[42:43], off nt
	global_load_dword v91, v[44:45], off nt
	global_load_dword v92, v[66:67], off nt
	global_load_dword v93, v[68:69], off nt
	v_lshl_add_u64 v[36:37], v[28:29], 0, v[70:71]
	v_lshlrev_b64 v[38:39], 12, v[6:7]
	v_or_b32_e32 v6, s51, v30
	s_add_i32 s55, s39, 28
	v_lshl_add_u64 v[34:35], v[28:29], 0, v[74:75]
	global_load_dword v94, v[36:37], off nt
	global_load_dword v95, v[34:35], off nt
	v_lshlrev_b64 v[36:37], 12, v[6:7]
	v_or_b32_e32 v6, s53, v30
	v_lshl_add_u64 v[34:35], v[28:29], 0, v[38:39]
	v_lshlrev_b64 v[38:39], 12, v[6:7]
	v_or_b32_e32 v6, s55, v30
	v_lshlrev_b64 v[40:41], 12, v[6:7]
	v_lshl_add_u64 v[40:41], v[28:29], 0, v[40:41]
	v_lshl_add_u64 v[36:37], v[28:29], 0, v[36:37]
	v_lshl_add_u64 v[38:39], v[28:29], 0, v[38:39]
	global_load_dword v6, v[40:41], off nt
	global_load_dword v96, v[38:39], off nt
	global_load_dword v97, v[36:37], off nt
	global_load_dword v98, v[34:35], off nt
	v_or_b32_e32 v36, s27, v1
	v_or_b32_e32 v34, s39, v2
	s_add_i32 s23, s23, 16
	s_add_i32 s22, s22, 16
	s_add_i32 s26, s26, -16
	v_mad_u64_u32 v[34:35], s[40:41], v34, s25, v[4:5]
	v_mad_u64_u32 v[36:37], s[40:41], v36, s25, v[4:5]
	v_or_b32_e32 v35, s42, v1
	v_or_b32_e32 v37, s43, v2
	v_or_b32_e32 v44, s44, v1
	v_or_b32_e32 v42, s45, v2
	v_or_b32_e32 v68, s46, v1
	v_or_b32_e32 v66, s47, v2
	v_or_b32_e32 v72, s48, v1
	v_or_b32_e32 v70, s49, v2
	v_or_b32_e32 v76, s50, v1
	v_or_b32_e32 v74, s51, v2
	v_or_b32_e32 v80, s52, v1
	v_or_b32_e32 v78, s53, v2
	v_or_b32_e32 v84, s54, v1
	v_or_b32_e32 v82, s55, v2
	s_cmp_lg_u32 s26, 0
	v_mad_u64_u32 v[38:39], s[40:41], v37, s25, v[4:5]
	v_mad_u64_u32 v[40:41], s[40:41], v35, s25, v[4:5]
	v_mad_u64_u32 v[42:43], s[40:41], v42, s25, v[4:5]
	v_mad_u64_u32 v[44:45], s[40:41], v44, s25, v[4:5]
	v_mad_u64_u32 v[66:67], s[40:41], v66, s25, v[4:5]
	v_mad_u64_u32 v[68:69], s[40:41], v68, s25, v[4:5]
	v_mad_u64_u32 v[70:71], s[40:41], v70, s25, v[4:5]
	v_mad_u64_u32 v[72:73], s[40:41], v72, s25, v[4:5]
	v_mad_u64_u32 v[74:75], s[40:41], v74, s25, v[4:5]
	v_mad_u64_u32 v[76:77], s[40:41], v76, s25, v[4:5]
	v_mad_u64_u32 v[78:79], s[40:41], v78, s25, v[4:5]
	v_mad_u64_u32 v[80:81], s[40:41], v80, s25, v[4:5]
	v_mad_u64_u32 v[82:83], s[40:41], v82, s25, v[4:5]
	v_mad_u64_u32 v[84:85], s[40:41], v84, s25, v[4:5]
	s_waitcnt vmcnt(15)
	ds_write_b32 v34, v33
	s_waitcnt vmcnt(14)
	ds_write_b32 v36, v65
	s_waitcnt vmcnt(13)
	ds_write_b32 v38, v86
	s_waitcnt vmcnt(12)
	ds_write_b32 v40, v87
	s_waitcnt vmcnt(4)
	ds_write_b32 v42, v95
	ds_write_b32 v44, v88
	ds_write_b32 v66, v94
	ds_write_b32 v68, v89
	s_waitcnt vmcnt(0)
	ds_write_b32 v70, v98
	ds_write_b32 v72, v90
	ds_write_b32 v74, v97
	ds_write_b32 v76, v91
	ds_write_b32 v78, v96
	ds_write_b32 v80, v92
	ds_write_b32 v82, v6
	ds_write_b32 v84, v93
	s_cbranch_scc1 .LBB0_103
	s_waitcnt lgkmcnt(0)
	ds_read2_b32 v[28:29], v48 offset1:33
	s_waitcnt lgkmcnt(0)
	v_cvt_pk_bf16_f32 v34, v28, v29
	ds_read2_b32 v[28:29], v48 offset0:66 offset1:99
	s_waitcnt lgkmcnt(0)
	v_cvt_pk_bf16_f32 v35, v28, v29
	ds_read2_b32 v[28:29], v48 offset0:132 offset1:165
	v_lshlrev_b32_e32 v6, 1, v32
	v_or_b32_e32 v3, v31, v47
	s_waitcnt lgkmcnt(0)
	v_cvt_pk_bf16_f32 v36, v28, v29
	ds_read2_b32 v[28:29], v48 offset0:198 offset1:231
	v_lshl_add_u64 v[38:39], v[14:15], 0, v[6:7]
	v_lshlrev_b32_e32 v6, 11, v3
	s_waitcnt lgkmcnt(0)
	v_cvt_pk_bf16_f32 v37, v28, v29
	ds_read2_b32 v[28:29], v48 offset0:8 offset1:41
	v_lshl_add_u64 v[32:33], v[38:39], 0, v[6:7]
	global_store_dwordx4 v[32:33], v[34:37], off nt
	s_waitcnt lgkmcnt(0)
	v_cvt_pk_bf16_f32 v32, v28, v29
	ds_read2_b32 v[28:29], v48 offset0:74 offset1:107
	s_waitcnt lgkmcnt(0)
	v_cvt_pk_bf16_f32 v33, v28, v29
	ds_read2_b32 v[28:29], v48 offset0:140 offset1:173
	v_or_b32_e32 v3, v31, v49
	s_waitcnt lgkmcnt(0)
	v_cvt_pk_bf16_f32 v34, v28, v29
	ds_read2_b32 v[28:29], v48 offset0:206 offset1:239
	v_lshlrev_b32_e32 v6, 11, v3
	s_waitcnt lgkmcnt(0)
	v_cvt_pk_bf16_f32 v35, v28, v29
	ds_read2_b32 v[28:29], v48 offset0:16 offset1:49
	v_lshl_add_u64 v[36:37], v[38:39], 0, v[6:7]
	global_store_dwordx4 v[36:37], v[32:35], off nt
	v_or_b32_e32 v3, v31, v50
	v_lshlrev_b32_e32 v6, 11, v3
	s_waitcnt lgkmcnt(0)
	v_cvt_pk_bf16_f32 v32, v28, v29
	ds_read2_b32 v[28:29], v48 offset0:82 offset1:115
	s_waitcnt lgkmcnt(0)
	v_cvt_pk_bf16_f32 v33, v28, v29
	ds_read2_b32 v[28:29], v48 offset0:148 offset1:181
	s_waitcnt lgkmcnt(0)
	v_cvt_pk_bf16_f32 v34, v28, v29
	ds_read2_b32 v[28:29], v48 offset0:214 offset1:247
	s_waitcnt lgkmcnt(0)
	v_cvt_pk_bf16_f32 v35, v28, v29
	ds_read2_b32 v[28:29], v48 offset0:24 offset1:57
	v_lshl_add_u64 v[36:37], v[38:39], 0, v[6:7]
	global_store_dwordx4 v[36:37], v[32:35], off nt
	s_waitcnt lgkmcnt(0)
	v_cvt_pk_bf16_f32 v28, v28, v29
	ds_read2_b32 v[32:33], v48 offset0:90 offset1:123
	s_waitcnt lgkmcnt(0)
	v_cvt_pk_bf16_f32 v29, v32, v33
	ds_read2_b32 v[32:33], v48 offset0:156 offset1:189
	v_or_b32_e32 v3, v31, v51
	s_waitcnt lgkmcnt(0)
	v_cvt_pk_bf16_f32 v30, v32, v33
	ds_read2_b32 v[32:33], v48 offset0:222 offset1:255
	v_lshlrev_b32_e32 v6, 11, v3
	s_waitcnt lgkmcnt(0)
	v_cvt_pk_bf16_f32 v31, v32, v33
	v_lshl_add_u64 v[32:33], v[38:39], 0, v[6:7]
	global_store_dwordx4 v[32:33], v[28:31], off nt
	s_waitcnt lgkmcnt(0)

.LBB0_108:
	s_lshl_b32 s26, s21, 1
	s_lshl_b32 s23, s20, 1
	v_or_b32_e32 v6, s26, v30
	s_add_i32 s40, s26, 4
	s_add_i32 s39, s23, 4
	s_add_i32 s41, s23, 8
	s_add_i32 s42, s26, 8
	v_lshlrev_b64 v[70:71], 12, v[6:7]
	v_or_b32_e32 v6, s40, v30
	v_mov_b32_e32 v35, v7
	v_mov_b32_e32 v37, v7
	v_mov_b32_e32 v39, v7
	v_or_b32_e32 v34, s23, v3
	s_add_i32 s43, s23, 12
	s_add_i32 s44, s26, 12
	s_add_i32 s45, s23, 16
	s_add_i32 s47, s23, 20
	s_add_i32 s49, s23, 24
	s_add_i32 s51, s23, 28
	v_or_b32_e32 v36, s39, v3
	v_or_b32_e32 v38, s41, v3
	v_lshlrev_b64 v[72:73], 12, v[6:7]
	v_or_b32_e32 v6, s42, v30
	v_mov_b32_e32 v41, v7
	v_mov_b32_e32 v43, v7
	v_mov_b32_e32 v45, v7
	v_mov_b32_e32 v67, v7
	v_mov_b32_e32 v69, v7
	s_add_i32 s46, s26, 16
	v_lshlrev_b64 v[34:35], 12, v[34:35]
	v_or_b32_e32 v40, s43, v3
	v_or_b32_e32 v42, s45, v3
	v_or_b32_e32 v44, s47, v3
	v_or_b32_e32 v66, s49, v3
	v_or_b32_e32 v68, s51, v3
	v_lshl_add_u64 v[70:71], v[28:29], 0, v[70:71]
	v_lshlrev_b64 v[36:37], 12, v[36:37]
	v_lshlrev_b64 v[38:39], 12, v[38:39]
	v_lshlrev_b64 v[74:75], 12, v[6:7]
	v_or_b32_e32 v6, s44, v30
	s_add_i32 s48, s26, 20
	v_lshl_add_u64 v[34:35], v[28:29], 0, v[34:35]
	v_lshlrev_b64 v[40:41], 12, v[40:41]
	v_lshlrev_b64 v[42:43], 12, v[42:43]
	v_lshlrev_b64 v[44:45], 12, v[44:45]
	v_lshlrev_b64 v[66:67], 12, v[66:67]
	v_lshlrev_b64 v[68:69], 12, v[68:69]
	v_lshl_add_u64 v[72:73], v[28:29], 0, v[72:73]
	v_lshl_add_u64 v[36:37], v[28:29], 0, v[36:37]
	v_lshl_add_u64 v[38:39], v[28:29], 0, v[38:39]
	global_load_dword v33, v[70:71], off nt
	global_load_dword v65, v[34:35], off nt
	v_lshlrev_b64 v[70:71], 12, v[6:7]
	v_or_b32_e32 v6, s46, v30
	s_add_i32 s50, s26, 24
	v_lshl_add_u64 v[40:41], v[28:29], 0, v[40:41]
	v_lshl_add_u64 v[42:43], v[28:29], 0, v[42:43]
	v_lshl_add_u64 v[44:45], v[28:29], 0, v[44:45]
	v_lshl_add_u64 v[66:67], v[28:29], 0, v[66:67]
	v_lshl_add_u64 v[68:69], v[28:29], 0, v[68:69]
	global_load_dword v86, v[72:73], off nt
	global_load_dword v87, v[36:37], off nt
	global_load_dword v88, v[38:39], off nt
	global_load_dword v89, v[40:41], off nt
	global_load_dword v90, v[42:43], off nt
	global_load_dword v91, v[44:45], off nt
	global_load_dword v92, v[66:67], off nt
	global_load_dword v93, v[68:69], off nt
	v_lshl_add_u64 v[36:37], v[28:29], 0, v[70:71]
	v_lshlrev_b64 v[38:39], 12, v[6:7]
	v_or_b32_e32 v6, s48, v30
	s_add_i32 s52, s26, 28
	v_lshl_add_u64 v[34:35], v[28:29], 0, v[74:75]
	global_load_dword v94, v[36:37], off nt
	global_load_dword v95, v[34:35], off nt
	v_lshlrev_b64 v[36:37], 12, v[6:7]
	v_or_b32_e32 v6, s50, v30
	v_lshl_add_u64 v[34:35], v[28:29], 0, v[38:39]
	v_lshlrev_b64 v[38:39], 12, v[6:7]
	v_or_b32_e32 v6, s52, v30
	v_lshlrev_b64 v[40:41], 12, v[6:7]
	v_lshl_add_u64 v[40:41], v[28:29], 0, v[40:41]
	v_lshl_add_u64 v[36:37], v[28:29], 0, v[36:37]
	v_lshl_add_u64 v[38:39], v[28:29], 0, v[38:39]
	global_load_dword v6, v[40:41], off nt
	global_load_dword v96, v[38:39], off nt
	global_load_dword v97, v[36:37], off nt
	global_load_dword v98, v[34:35], off nt
	v_or_b32_e32 v36, s23, v1
	v_or_b32_e32 v34, s26, v2
	s_add_i32 s21, s21, 16
	s_add_i32 s20, s20, 16
	s_add_i32 s22, s22, -16
	v_mad_u64_u32 v[34:35], s[26:27], v34, s25, v[4:5]
	v_mad_u64_u32 v[36:37], s[26:27], v36, s25, v[4:5]
	v_or_b32_e32 v35, s39, v1
	v_or_b32_e32 v37, s40, v2
	v_or_b32_e32 v44, s41, v1
	v_or_b32_e32 v42, s42, v2
	v_or_b32_e32 v68, s43, v1
	v_or_b32_e32 v66, s44, v2
	v_or_b32_e32 v72, s45, v1
	v_or_b32_e32 v70, s46, v2
	v_or_b32_e32 v76, s47, v1
	v_or_b32_e32 v74, s48, v2
	v_or_b32_e32 v80, s49, v1
	v_or_b32_e32 v78, s50, v2
	v_or_b32_e32 v84, s51, v1
	v_or_b32_e32 v82, s52, v2
	s_cmp_lg_u32 s22, 0
	v_mad_u64_u32 v[38:39], s[26:27], v37, s25, v[4:5]
	v_mad_u64_u32 v[40:41], s[26:27], v35, s25, v[4:5]
	v_mad_u64_u32 v[42:43], s[26:27], v42, s25, v[4:5]
	v_mad_u64_u32 v[44:45], s[26:27], v44, s25, v[4:5]
	v_mad_u64_u32 v[66:67], s[26:27], v66, s25, v[4:5]
	v_mad_u64_u32 v[68:69], s[26:27], v68, s25, v[4:5]
	v_mad_u64_u32 v[70:71], s[26:27], v70, s25, v[4:5]
	v_mad_u64_u32 v[72:73], s[26:27], v72, s25, v[4:5]
	v_mad_u64_u32 v[74:75], s[26:27], v74, s25, v[4:5]
	v_mad_u64_u32 v[76:77], s[26:27], v76, s25, v[4:5]
	v_mad_u64_u32 v[78:79], s[26:27], v78, s25, v[4:5]
	v_mad_u64_u32 v[80:81], s[26:27], v80, s25, v[4:5]
	v_mad_u64_u32 v[82:83], s[26:27], v82, s25, v[4:5]
	v_mad_u64_u32 v[84:85], s[26:27], v84, s25, v[4:5]
	s_waitcnt vmcnt(15)
	ds_write_b32 v34, v33
	s_waitcnt vmcnt(14)
	ds_write_b32 v36, v65
	s_waitcnt vmcnt(13)
	ds_write_b32 v38, v86
	s_waitcnt vmcnt(12)
	ds_write_b32 v40, v87
	s_waitcnt vmcnt(4)
	ds_write_b32 v42, v95
	ds_write_b32 v44, v88
	ds_write_b32 v66, v94
	ds_write_b32 v68, v89
	s_waitcnt vmcnt(0)
	ds_write_b32 v70, v98
	ds_write_b32 v72, v90
	ds_write_b32 v74, v97
	ds_write_b32 v76, v91
	ds_write_b32 v78, v96
	ds_write_b32 v80, v92
	ds_write_b32 v82, v6
	ds_write_b32 v84, v93
	s_cbranch_scc1 .LBB0_108
	s_waitcnt lgkmcnt(0)
	ds_read2_b32 v[28:29], v48 offset1:33
	s_waitcnt lgkmcnt(0)
	v_cvt_pk_bf16_f32 v34, v28, v29
	ds_read2_b32 v[28:29], v48 offset0:66 offset1:99
	s_waitcnt lgkmcnt(0)
	v_cvt_pk_bf16_f32 v35, v28, v29
	ds_read2_b32 v[28:29], v48 offset0:132 offset1:165
	v_lshlrev_b32_e32 v6, 1, v32
	v_or_b32_e32 v3, v31, v47
	s_waitcnt lgkmcnt(0)
	v_cvt_pk_bf16_f32 v36, v28, v29
	ds_read2_b32 v[28:29], v48 offset0:198 offset1:231
	v_lshl_add_u64 v[38:39], v[16:17], 0, v[6:7]
	v_lshlrev_b32_e32 v6, 10, v3
	s_waitcnt lgkmcnt(0)
	v_cvt_pk_bf16_f32 v37, v28, v29
	ds_read2_b32 v[28:29], v48 offset0:8 offset1:41
	v_lshl_add_u64 v[32:33], v[38:39], 0, v[6:7]
	global_store_dwordx4 v[32:33], v[34:37], off nt
	s_waitcnt lgkmcnt(0)
	v_cvt_pk_bf16_f32 v32, v28, v29
	ds_read2_b32 v[28:29], v48 offset0:74 offset1:107
	s_waitcnt lgkmcnt(0)
	v_cvt_pk_bf16_f32 v33, v28, v29
	ds_read2_b32 v[28:29], v48 offset0:140 offset1:173
	v_or_b32_e32 v3, v31, v49
	s_waitcnt lgkmcnt(0)
	v_cvt_pk_bf16_f32 v34, v28, v29
	ds_read2_b32 v[28:29], v48 offset0:206 offset1:239
	v_lshlrev_b32_e32 v6, 10, v3
	s_waitcnt lgkmcnt(0)
	v_cvt_pk_bf16_f32 v35, v28, v29
	ds_read2_b32 v[28:29], v48 offset0:16 offset1:49
	v_lshl_add_u64 v[36:37], v[38:39], 0, v[6:7]
	global_store_dwordx4 v[36:37], v[32:35], off nt
	v_or_b32_e32 v3, v31, v50
	v_lshlrev_b32_e32 v6, 10, v3
	s_waitcnt lgkmcnt(0)
	v_cvt_pk_bf16_f32 v32, v28, v29
	ds_read2_b32 v[28:29], v48 offset0:82 offset1:115
	s_waitcnt lgkmcnt(0)
	v_cvt_pk_bf16_f32 v33, v28, v29
	ds_read2_b32 v[28:29], v48 offset0:148 offset1:181
	s_waitcnt lgkmcnt(0)
	v_cvt_pk_bf16_f32 v34, v28, v29
	ds_read2_b32 v[28:29], v48 offset0:214 offset1:247
	s_waitcnt lgkmcnt(0)
	v_cvt_pk_bf16_f32 v35, v28, v29
	ds_read2_b32 v[28:29], v48 offset0:24 offset1:57
	v_lshl_add_u64 v[36:37], v[38:39], 0, v[6:7]
	global_store_dwordx4 v[36:37], v[32:35], off nt
	s_waitcnt lgkmcnt(0)
	v_cvt_pk_bf16_f32 v28, v28, v29
	ds_read2_b32 v[32:33], v48 offset0:90 offset1:123
	s_waitcnt lgkmcnt(0)
	v_cvt_pk_bf16_f32 v29, v32, v33
	ds_read2_b32 v[32:33], v48 offset0:156 offset1:189
	v_or_b32_e32 v3, v31, v51
	s_waitcnt lgkmcnt(0)
	v_cvt_pk_bf16_f32 v30, v32, v33
	ds_read2_b32 v[32:33], v48 offset0:222 offset1:255
	v_lshlrev_b32_e32 v6, 10, v3
	s_waitcnt lgkmcnt(0)
	v_cvt_pk_bf16_f32 v31, v32, v33
	v_lshl_add_u64 v[32:33], v[38:39], 0, v[6:7]
	global_store_dwordx4 v[32:33], v[28:31], off nt
	s_waitcnt lgkmcnt(0)

.LBB0_113:
	s_lshl_b32 s22, s19, 1
	s_lshl_b32 s21, s18, 1
	v_or_b32_e32 v6, s22, v30
	s_add_i32 s27, s22, 4
	s_add_i32 s26, s21, 4
	s_add_i32 s39, s21, 8
	s_add_i32 s40, s22, 8
	v_lshlrev_b64 v[70:71], 12, v[6:7]
	v_or_b32_e32 v6, s27, v30
	v_mov_b32_e32 v35, v7
	v_mov_b32_e32 v37, v7
	v_mov_b32_e32 v39, v7
	v_or_b32_e32 v34, s21, v3
	s_add_i32 s41, s21, 12
	s_add_i32 s42, s22, 12
	s_add_i32 s43, s21, 16
	s_add_i32 s45, s21, 20
	s_add_i32 s47, s21, 24
	s_add_i32 s49, s21, 28
	v_or_b32_e32 v36, s26, v3
	v_or_b32_e32 v38, s39, v3
	v_lshlrev_b64 v[72:73], 12, v[6:7]
	v_or_b32_e32 v6, s40, v30
	v_mov_b32_e32 v41, v7
	v_mov_b32_e32 v43, v7
	v_mov_b32_e32 v45, v7
	v_mov_b32_e32 v67, v7
	v_mov_b32_e32 v69, v7
	s_add_i32 s44, s22, 16
	v_lshlrev_b64 v[34:35], 12, v[34:35]
	v_or_b32_e32 v40, s41, v3
	v_or_b32_e32 v42, s43, v3
	v_or_b32_e32 v44, s45, v3
	v_or_b32_e32 v66, s47, v3
	v_or_b32_e32 v68, s49, v3
	v_lshl_add_u64 v[70:71], v[28:29], 0, v[70:71]
	v_lshlrev_b64 v[36:37], 12, v[36:37]
	v_lshlrev_b64 v[38:39], 12, v[38:39]
	v_lshlrev_b64 v[74:75], 12, v[6:7]
	v_or_b32_e32 v6, s42, v30
	s_add_i32 s46, s22, 20
	v_lshl_add_u64 v[34:35], v[28:29], 0, v[34:35]
	v_lshlrev_b64 v[40:41], 12, v[40:41]
	v_lshlrev_b64 v[42:43], 12, v[42:43]
	v_lshlrev_b64 v[44:45], 12, v[44:45]
	v_lshlrev_b64 v[66:67], 12, v[66:67]
	v_lshlrev_b64 v[68:69], 12, v[68:69]
	v_lshl_add_u64 v[72:73], v[28:29], 0, v[72:73]
	v_lshl_add_u64 v[36:37], v[28:29], 0, v[36:37]
	v_lshl_add_u64 v[38:39], v[28:29], 0, v[38:39]
	global_load_dword v33, v[70:71], off nt
	global_load_dword v65, v[34:35], off nt
	v_lshlrev_b64 v[70:71], 12, v[6:7]
	v_or_b32_e32 v6, s44, v30
	s_add_i32 s48, s22, 24
	v_lshl_add_u64 v[40:41], v[28:29], 0, v[40:41]
	v_lshl_add_u64 v[42:43], v[28:29], 0, v[42:43]
	v_lshl_add_u64 v[44:45], v[28:29], 0, v[44:45]
	v_lshl_add_u64 v[66:67], v[28:29], 0, v[66:67]
	v_lshl_add_u64 v[68:69], v[28:29], 0, v[68:69]
	global_load_dword v86, v[72:73], off nt
	global_load_dword v87, v[36:37], off nt
	global_load_dword v88, v[38:39], off nt
	global_load_dword v89, v[40:41], off nt
	global_load_dword v90, v[42:43], off nt
	global_load_dword v91, v[44:45], off nt
	global_load_dword v92, v[66:67], off nt
	global_load_dword v93, v[68:69], off nt
	v_lshl_add_u64 v[36:37], v[28:29], 0, v[70:71]
	v_lshlrev_b64 v[38:39], 12, v[6:7]
	v_or_b32_e32 v6, s46, v30
	s_add_i32 s50, s22, 28
	v_lshl_add_u64 v[34:35], v[28:29], 0, v[74:75]
	global_load_dword v94, v[36:37], off nt
	global_load_dword v95, v[34:35], off nt
	v_lshlrev_b64 v[36:37], 12, v[6:7]
	v_or_b32_e32 v6, s48, v30
	v_lshl_add_u64 v[34:35], v[28:29], 0, v[38:39]
	v_lshlrev_b64 v[38:39], 12, v[6:7]
	v_or_b32_e32 v6, s50, v30
	v_lshlrev_b64 v[40:41], 12, v[6:7]
	v_lshl_add_u64 v[40:41], v[28:29], 0, v[40:41]
	v_lshl_add_u64 v[36:37], v[28:29], 0, v[36:37]
	v_lshl_add_u64 v[38:39], v[28:29], 0, v[38:39]
	global_load_dword v6, v[40:41], off nt
	global_load_dword v96, v[38:39], off nt
	global_load_dword v97, v[36:37], off nt
	global_load_dword v98, v[34:35], off nt
	v_or_b32_e32 v36, s21, v1
	v_or_b32_e32 v34, s22, v2
	s_add_i32 s19, s19, 16
	s_add_i32 s18, s18, 16
	s_add_i32 s20, s20, -16
	v_mad_u64_u32 v[34:35], s[22:23], v34, s25, v[4:5]
	v_mad_u64_u32 v[36:37], s[22:23], v36, s25, v[4:5]
	v_or_b32_e32 v35, s26, v1
	v_or_b32_e32 v37, s27, v2
	v_or_b32_e32 v44, s39, v1
	v_or_b32_e32 v42, s40, v2
	v_or_b32_e32 v68, s41, v1
	v_or_b32_e32 v66, s42, v2
	v_or_b32_e32 v72, s43, v1
	v_or_b32_e32 v70, s44, v2
	v_or_b32_e32 v76, s45, v1
	v_or_b32_e32 v74, s46, v2
	v_or_b32_e32 v80, s47, v1
	v_or_b32_e32 v78, s48, v2
	v_or_b32_e32 v84, s49, v1
	v_or_b32_e32 v82, s50, v2
	s_cmp_lg_u32 s20, 0
	v_mad_u64_u32 v[38:39], s[22:23], v37, s25, v[4:5]
	v_mad_u64_u32 v[40:41], s[22:23], v35, s25, v[4:5]
	v_mad_u64_u32 v[42:43], s[22:23], v42, s25, v[4:5]
	v_mad_u64_u32 v[44:45], s[22:23], v44, s25, v[4:5]
	v_mad_u64_u32 v[66:67], s[22:23], v66, s25, v[4:5]
	v_mad_u64_u32 v[68:69], s[22:23], v68, s25, v[4:5]
	v_mad_u64_u32 v[70:71], s[22:23], v70, s25, v[4:5]
	v_mad_u64_u32 v[72:73], s[22:23], v72, s25, v[4:5]
	v_mad_u64_u32 v[74:75], s[22:23], v74, s25, v[4:5]
	v_mad_u64_u32 v[76:77], s[22:23], v76, s25, v[4:5]
	v_mad_u64_u32 v[78:79], s[22:23], v78, s25, v[4:5]
	v_mad_u64_u32 v[80:81], s[22:23], v80, s25, v[4:5]
	v_mad_u64_u32 v[82:83], s[22:23], v82, s25, v[4:5]
	v_mad_u64_u32 v[84:85], s[22:23], v84, s25, v[4:5]
	s_waitcnt vmcnt(15)
	ds_write_b32 v34, v33
	s_waitcnt vmcnt(14)
	ds_write_b32 v36, v65
	s_waitcnt vmcnt(13)
	ds_write_b32 v38, v86
	s_waitcnt vmcnt(12)
	ds_write_b32 v40, v87
	s_waitcnt vmcnt(4)
	ds_write_b32 v42, v95
	ds_write_b32 v44, v88
	ds_write_b32 v66, v94
	ds_write_b32 v68, v89
	s_waitcnt vmcnt(0)
	ds_write_b32 v70, v98
	ds_write_b32 v72, v90
	ds_write_b32 v74, v97
	ds_write_b32 v76, v91
	ds_write_b32 v78, v96
	ds_write_b32 v80, v92
	ds_write_b32 v82, v6
	ds_write_b32 v84, v93
	s_cbranch_scc1 .LBB0_113
	s_waitcnt lgkmcnt(0)
	ds_read2_b32 v[28:29], v48 offset1:33
	s_waitcnt lgkmcnt(0)
	v_cvt_pk_bf16_f32 v34, v28, v29
	ds_read2_b32 v[28:29], v48 offset0:66 offset1:99
	s_waitcnt lgkmcnt(0)
	v_cvt_pk_bf16_f32 v35, v28, v29
	ds_read2_b32 v[28:29], v48 offset0:132 offset1:165
	v_lshlrev_b32_e32 v6, 1, v32
	v_or_b32_e32 v3, v31, v47
	s_waitcnt lgkmcnt(0)
	v_cvt_pk_bf16_f32 v36, v28, v29
	ds_read2_b32 v[28:29], v48 offset0:198 offset1:231
	v_lshl_add_u64 v[38:39], v[18:19], 0, v[6:7]
	v_lshlrev_b32_e32 v6, 10, v3
	s_waitcnt lgkmcnt(0)
	v_cvt_pk_bf16_f32 v37, v28, v29
	ds_read2_b32 v[28:29], v48 offset0:8 offset1:41
	v_lshl_add_u64 v[32:33], v[38:39], 0, v[6:7]
	global_store_dwordx4 v[32:33], v[34:37], off nt
	s_waitcnt lgkmcnt(0)
	v_cvt_pk_bf16_f32 v32, v28, v29
	ds_read2_b32 v[28:29], v48 offset0:74 offset1:107
	s_waitcnt lgkmcnt(0)
	v_cvt_pk_bf16_f32 v33, v28, v29
	ds_read2_b32 v[28:29], v48 offset0:140 offset1:173
	v_or_b32_e32 v3, v31, v49
	s_waitcnt lgkmcnt(0)
	v_cvt_pk_bf16_f32 v34, v28, v29
	ds_read2_b32 v[28:29], v48 offset0:206 offset1:239
	v_lshlrev_b32_e32 v6, 10, v3
	s_waitcnt lgkmcnt(0)
	v_cvt_pk_bf16_f32 v35, v28, v29
	ds_read2_b32 v[28:29], v48 offset0:16 offset1:49
	v_lshl_add_u64 v[36:37], v[38:39], 0, v[6:7]
	global_store_dwordx4 v[36:37], v[32:35], off nt
	v_or_b32_e32 v3, v31, v50
	v_lshlrev_b32_e32 v6, 10, v3
	s_waitcnt lgkmcnt(0)
	v_cvt_pk_bf16_f32 v32, v28, v29
	ds_read2_b32 v[28:29], v48 offset0:82 offset1:115
	s_waitcnt lgkmcnt(0)
	v_cvt_pk_bf16_f32 v33, v28, v29
	ds_read2_b32 v[28:29], v48 offset0:148 offset1:181
	s_waitcnt lgkmcnt(0)
	v_cvt_pk_bf16_f32 v34, v28, v29
	ds_read2_b32 v[28:29], v48 offset0:214 offset1:247
	s_waitcnt lgkmcnt(0)
	v_cvt_pk_bf16_f32 v35, v28, v29
	ds_read2_b32 v[28:29], v48 offset0:24 offset1:57
	v_lshl_add_u64 v[36:37], v[38:39], 0, v[6:7]
	global_store_dwordx4 v[36:37], v[32:35], off nt
	s_waitcnt lgkmcnt(0)
	v_cvt_pk_bf16_f32 v28, v28, v29
	ds_read2_b32 v[32:33], v48 offset0:90 offset1:123
	s_waitcnt lgkmcnt(0)
	v_cvt_pk_bf16_f32 v29, v32, v33
	ds_read2_b32 v[32:33], v48 offset0:156 offset1:189
	v_or_b32_e32 v3, v31, v51
	s_waitcnt lgkmcnt(0)
	v_cvt_pk_bf16_f32 v30, v32, v33
	ds_read2_b32 v[32:33], v48 offset0:222 offset1:255
	v_lshlrev_b32_e32 v6, 10, v3
	s_waitcnt lgkmcnt(0)
	v_cvt_pk_bf16_f32 v31, v32, v33
	v_lshl_add_u64 v[32:33], v[38:39], 0, v[6:7]
	global_store_dwordx4 v[32:33], v[28:31], off nt
	s_waitcnt lgkmcnt(0)

.LBB0_118:
	s_lshl_b32 s20, s18, 1
	s_lshl_b32 s19, s17, 1
	v_or_b32_e32 v6, s20, v30
	s_add_i32 s23, s20, 4
	s_add_i32 s22, s19, 4
	s_add_i32 s26, s19, 8
	s_add_i32 s27, s20, 8
	v_lshlrev_b64 v[70:71], 12, v[6:7]
	v_or_b32_e32 v6, s23, v30
	v_mov_b32_e32 v35, v7
	v_mov_b32_e32 v37, v7
	v_mov_b32_e32 v39, v7
	v_or_b32_e32 v34, s19, v3
	s_add_i32 s39, s19, 12
	s_add_i32 s40, s20, 12
	s_add_i32 s41, s19, 16
	s_add_i32 s43, s19, 20
	s_add_i32 s45, s19, 24
	s_add_i32 s47, s19, 28
	v_or_b32_e32 v36, s22, v3
	v_or_b32_e32 v38, s26, v3
	v_lshlrev_b64 v[72:73], 12, v[6:7]
	v_or_b32_e32 v6, s27, v30
	v_mov_b32_e32 v41, v7
	v_mov_b32_e32 v43, v7
	v_mov_b32_e32 v45, v7
	v_mov_b32_e32 v67, v7
	v_mov_b32_e32 v69, v7
	s_add_i32 s42, s20, 16
	v_lshlrev_b64 v[34:35], 12, v[34:35]
	v_or_b32_e32 v40, s39, v3
	v_or_b32_e32 v42, s41, v3
	v_or_b32_e32 v44, s43, v3
	v_or_b32_e32 v66, s45, v3
	v_or_b32_e32 v68, s47, v3
	v_lshl_add_u64 v[70:71], v[28:29], 0, v[70:71]
	v_lshlrev_b64 v[36:37], 12, v[36:37]
	v_lshlrev_b64 v[38:39], 12, v[38:39]
	v_lshlrev_b64 v[74:75], 12, v[6:7]
	v_or_b32_e32 v6, s40, v30
	s_add_i32 s44, s20, 20
	v_lshl_add_u64 v[34:35], v[28:29], 0, v[34:35]
	v_lshlrev_b64 v[40:41], 12, v[40:41]
	v_lshlrev_b64 v[42:43], 12, v[42:43]
	v_lshlrev_b64 v[44:45], 12, v[44:45]
	v_lshlrev_b64 v[66:67], 12, v[66:67]
	v_lshlrev_b64 v[68:69], 12, v[68:69]
	v_lshl_add_u64 v[72:73], v[28:29], 0, v[72:73]
	v_lshl_add_u64 v[36:37], v[28:29], 0, v[36:37]
	v_lshl_add_u64 v[38:39], v[28:29], 0, v[38:39]
	global_load_dword v33, v[70:71], off nt
	global_load_dword v65, v[34:35], off nt
	v_lshlrev_b64 v[70:71], 12, v[6:7]
	v_or_b32_e32 v6, s42, v30
	s_add_i32 s46, s20, 24
	v_lshl_add_u64 v[40:41], v[28:29], 0, v[40:41]
	v_lshl_add_u64 v[42:43], v[28:29], 0, v[42:43]
	v_lshl_add_u64 v[44:45], v[28:29], 0, v[44:45]
	v_lshl_add_u64 v[66:67], v[28:29], 0, v[66:67]
	v_lshl_add_u64 v[68:69], v[28:29], 0, v[68:69]
	global_load_dword v86, v[72:73], off nt
	global_load_dword v87, v[36:37], off nt
	global_load_dword v88, v[38:39], off nt
	global_load_dword v89, v[40:41], off nt
	global_load_dword v90, v[42:43], off nt
	global_load_dword v91, v[44:45], off nt
	global_load_dword v92, v[66:67], off nt
	global_load_dword v93, v[68:69], off nt
	v_lshl_add_u64 v[36:37], v[28:29], 0, v[70:71]
	v_lshlrev_b64 v[38:39], 12, v[6:7]
	v_or_b32_e32 v6, s44, v30
	s_add_i32 s48, s20, 28
	v_lshl_add_u64 v[34:35], v[28:29], 0, v[74:75]
	global_load_dword v94, v[36:37], off nt
	global_load_dword v95, v[34:35], off nt
	v_lshlrev_b64 v[36:37], 12, v[6:7]
	v_or_b32_e32 v6, s46, v30
	v_lshl_add_u64 v[34:35], v[28:29], 0, v[38:39]
	v_lshlrev_b64 v[38:39], 12, v[6:7]
	v_or_b32_e32 v6, s48, v30
	v_lshlrev_b64 v[40:41], 12, v[6:7]
	v_lshl_add_u64 v[40:41], v[28:29], 0, v[40:41]
	v_lshl_add_u64 v[36:37], v[28:29], 0, v[36:37]
	v_lshl_add_u64 v[38:39], v[28:29], 0, v[38:39]
	global_load_dword v6, v[40:41], off nt
	global_load_dword v96, v[38:39], off nt
	global_load_dword v97, v[36:37], off nt
	global_load_dword v98, v[34:35], off nt
	v_or_b32_e32 v36, s19, v1
	v_or_b32_e32 v34, s20, v2
	s_add_i32 s18, s18, 16
	s_add_i32 s17, s17, 16
	s_add_i32 s16, s16, -16
	v_mad_u64_u32 v[34:35], s[20:21], v34, s25, v[4:5]
	v_mad_u64_u32 v[36:37], s[20:21], v36, s25, v[4:5]
	v_or_b32_e32 v35, s22, v1
	v_or_b32_e32 v37, s23, v2
	v_or_b32_e32 v44, s26, v1
	v_or_b32_e32 v42, s27, v2
	v_or_b32_e32 v68, s39, v1
	v_or_b32_e32 v66, s40, v2
	v_or_b32_e32 v72, s41, v1
	v_or_b32_e32 v70, s42, v2
	v_or_b32_e32 v76, s43, v1
	v_or_b32_e32 v74, s44, v2
	v_or_b32_e32 v80, s45, v1
	v_or_b32_e32 v78, s46, v2
	v_or_b32_e32 v84, s47, v1
	v_or_b32_e32 v82, s48, v2
	s_cmp_lg_u32 s16, 0
	v_mad_u64_u32 v[38:39], s[20:21], v37, s25, v[4:5]
	v_mad_u64_u32 v[40:41], s[20:21], v35, s25, v[4:5]
	v_mad_u64_u32 v[42:43], s[20:21], v42, s25, v[4:5]
	v_mad_u64_u32 v[44:45], s[20:21], v44, s25, v[4:5]
	v_mad_u64_u32 v[66:67], s[20:21], v66, s25, v[4:5]
	v_mad_u64_u32 v[68:69], s[20:21], v68, s25, v[4:5]
	v_mad_u64_u32 v[70:71], s[20:21], v70, s25, v[4:5]
	v_mad_u64_u32 v[72:73], s[20:21], v72, s25, v[4:5]
	v_mad_u64_u32 v[74:75], s[20:21], v74, s25, v[4:5]
	v_mad_u64_u32 v[76:77], s[20:21], v76, s25, v[4:5]
	v_mad_u64_u32 v[78:79], s[20:21], v78, s25, v[4:5]
	v_mad_u64_u32 v[80:81], s[20:21], v80, s25, v[4:5]
	v_mad_u64_u32 v[82:83], s[20:21], v82, s25, v[4:5]
	v_mad_u64_u32 v[84:85], s[20:21], v84, s25, v[4:5]
	s_waitcnt vmcnt(15)
	ds_write_b32 v34, v33
	s_waitcnt vmcnt(14)
	ds_write_b32 v36, v65
	s_waitcnt vmcnt(13)
	ds_write_b32 v38, v86
	s_waitcnt vmcnt(12)
	ds_write_b32 v40, v87
	s_waitcnt vmcnt(4)
	ds_write_b32 v42, v95
	ds_write_b32 v44, v88
	ds_write_b32 v66, v94
	ds_write_b32 v68, v89
	s_waitcnt vmcnt(0)
	ds_write_b32 v70, v98
	ds_write_b32 v72, v90
	ds_write_b32 v74, v97
	ds_write_b32 v76, v91
	ds_write_b32 v78, v96
	ds_write_b32 v80, v92
	ds_write_b32 v82, v6
	ds_write_b32 v84, v93
	s_cbranch_scc1 .LBB0_118
	s_waitcnt lgkmcnt(0)
	ds_read2_b32 v[28:29], v48 offset1:33
	s_waitcnt lgkmcnt(0)
	v_cvt_pk_bf16_f32 v34, v28, v29
	ds_read2_b32 v[28:29], v48 offset0:66 offset1:99
	s_waitcnt lgkmcnt(0)
	v_cvt_pk_bf16_f32 v35, v28, v29
	ds_read2_b32 v[28:29], v48 offset0:132 offset1:165
	v_lshlrev_b32_e32 v6, 1, v32
	v_or_b32_e32 v3, v31, v47
	s_waitcnt lgkmcnt(0)
	v_cvt_pk_bf16_f32 v36, v28, v29
	ds_read2_b32 v[28:29], v48 offset0:198 offset1:231
	v_lshl_add_u64 v[38:39], v[20:21], 0, v[6:7]
	v_lshlrev_b32_e32 v6, 9, v3
	s_waitcnt lgkmcnt(0)
	v_cvt_pk_bf16_f32 v37, v28, v29
	ds_read2_b32 v[28:29], v48 offset0:8 offset1:41
	v_lshl_add_u64 v[32:33], v[38:39], 0, v[6:7]
	global_store_dwordx4 v[32:33], v[34:37], off nt
	s_waitcnt lgkmcnt(0)
	v_cvt_pk_bf16_f32 v32, v28, v29
	ds_read2_b32 v[28:29], v48 offset0:74 offset1:107
	s_waitcnt lgkmcnt(0)
	v_cvt_pk_bf16_f32 v33, v28, v29
	ds_read2_b32 v[28:29], v48 offset0:140 offset1:173
	v_or_b32_e32 v3, v31, v49
	s_waitcnt lgkmcnt(0)
	v_cvt_pk_bf16_f32 v34, v28, v29
	ds_read2_b32 v[28:29], v48 offset0:206 offset1:239
	v_lshlrev_b32_e32 v6, 9, v3
	s_waitcnt lgkmcnt(0)
	v_cvt_pk_bf16_f32 v35, v28, v29
	ds_read2_b32 v[28:29], v48 offset0:16 offset1:49
	v_lshl_add_u64 v[36:37], v[38:39], 0, v[6:7]
	global_store_dwordx4 v[36:37], v[32:35], off nt
	v_or_b32_e32 v3, v31, v50
	v_lshlrev_b32_e32 v6, 9, v3
	s_waitcnt lgkmcnt(0)
	v_cvt_pk_bf16_f32 v32, v28, v29
	ds_read2_b32 v[28:29], v48 offset0:82 offset1:115
	s_waitcnt lgkmcnt(0)
	v_cvt_pk_bf16_f32 v33, v28, v29
	ds_read2_b32 v[28:29], v48 offset0:148 offset1:181
	s_waitcnt lgkmcnt(0)
	v_cvt_pk_bf16_f32 v34, v28, v29
	ds_read2_b32 v[28:29], v48 offset0:214 offset1:247
	s_waitcnt lgkmcnt(0)
	v_cvt_pk_bf16_f32 v35, v28, v29
	ds_read2_b32 v[28:29], v48 offset0:24 offset1:57
	v_lshl_add_u64 v[36:37], v[38:39], 0, v[6:7]
	global_store_dwordx4 v[36:37], v[32:35], off nt
	s_waitcnt lgkmcnt(0)
	v_cvt_pk_bf16_f32 v28, v28, v29
	ds_read2_b32 v[32:33], v48 offset0:90 offset1:123
	s_waitcnt lgkmcnt(0)
	v_cvt_pk_bf16_f32 v29, v32, v33
	ds_read2_b32 v[32:33], v48 offset0:156 offset1:189
	v_or_b32_e32 v3, v31, v51
	s_waitcnt lgkmcnt(0)
	v_cvt_pk_bf16_f32 v30, v32, v33
	ds_read2_b32 v[32:33], v48 offset0:222 offset1:255
	v_lshlrev_b32_e32 v6, 9, v3
	s_waitcnt lgkmcnt(0)
	v_cvt_pk_bf16_f32 v31, v32, v33
	v_lshl_add_u64 v[32:33], v[38:39], 0, v[6:7]
	global_store_dwordx4 v[32:33], v[28:31], off nt
	s_waitcnt lgkmcnt(0)

.LBB0_123:
	s_lshl_b32 s18, s16, 1
	s_lshl_b32 s17, s15, 1
	v_or_b32_e32 v6, s18, v30
	s_add_i32 s21, s18, 4
	s_add_i32 s20, s17, 4
	s_add_i32 s22, s17, 8
	s_add_i32 s23, s18, 8
	v_lshlrev_b64 v[70:71], 12, v[6:7]
	v_or_b32_e32 v6, s21, v30
	v_mov_b32_e32 v35, v7
	v_mov_b32_e32 v37, v7
	v_mov_b32_e32 v39, v7
	v_or_b32_e32 v34, s17, v3
	s_add_i32 s26, s17, 12
	s_add_i32 s27, s18, 12
	s_add_i32 s39, s17, 16
	s_add_i32 s41, s17, 20
	s_add_i32 s43, s17, 24
	s_add_i32 s45, s17, 28
	v_or_b32_e32 v36, s20, v3
	v_or_b32_e32 v38, s22, v3
	v_lshlrev_b64 v[72:73], 12, v[6:7]
	v_or_b32_e32 v6, s23, v30
	v_mov_b32_e32 v41, v7
	v_mov_b32_e32 v43, v7
	v_mov_b32_e32 v45, v7
	v_mov_b32_e32 v67, v7
	v_mov_b32_e32 v69, v7
	s_add_i32 s40, s18, 16
	v_lshlrev_b64 v[34:35], 12, v[34:35]
	v_or_b32_e32 v40, s26, v3
	v_or_b32_e32 v42, s39, v3
	v_or_b32_e32 v44, s41, v3
	v_or_b32_e32 v66, s43, v3
	v_or_b32_e32 v68, s45, v3
	v_lshl_add_u64 v[70:71], v[28:29], 0, v[70:71]
	v_lshlrev_b64 v[36:37], 12, v[36:37]
	v_lshlrev_b64 v[38:39], 12, v[38:39]
	v_lshlrev_b64 v[74:75], 12, v[6:7]
	v_or_b32_e32 v6, s27, v30
	s_add_i32 s42, s18, 20
	v_lshl_add_u64 v[34:35], v[28:29], 0, v[34:35]
	v_lshlrev_b64 v[40:41], 12, v[40:41]
	v_lshlrev_b64 v[42:43], 12, v[42:43]
	v_lshlrev_b64 v[44:45], 12, v[44:45]
	v_lshlrev_b64 v[66:67], 12, v[66:67]
	v_lshlrev_b64 v[68:69], 12, v[68:69]
	v_lshl_add_u64 v[72:73], v[28:29], 0, v[72:73]
	v_lshl_add_u64 v[36:37], v[28:29], 0, v[36:37]
	v_lshl_add_u64 v[38:39], v[28:29], 0, v[38:39]
	global_load_dword v33, v[70:71], off nt
	global_load_dword v65, v[34:35], off nt
	v_lshlrev_b64 v[70:71], 12, v[6:7]
	v_or_b32_e32 v6, s40, v30
	s_add_i32 s44, s18, 24
	v_lshl_add_u64 v[40:41], v[28:29], 0, v[40:41]
	v_lshl_add_u64 v[42:43], v[28:29], 0, v[42:43]
	v_lshl_add_u64 v[44:45], v[28:29], 0, v[44:45]
	v_lshl_add_u64 v[66:67], v[28:29], 0, v[66:67]
	v_lshl_add_u64 v[68:69], v[28:29], 0, v[68:69]
	global_load_dword v86, v[72:73], off nt
	global_load_dword v87, v[36:37], off nt
	global_load_dword v88, v[38:39], off nt
	global_load_dword v89, v[40:41], off nt
	global_load_dword v90, v[42:43], off nt
	global_load_dword v91, v[44:45], off nt
	global_load_dword v92, v[66:67], off nt
	global_load_dword v93, v[68:69], off nt
	v_lshl_add_u64 v[36:37], v[28:29], 0, v[70:71]
	v_lshlrev_b64 v[38:39], 12, v[6:7]
	v_or_b32_e32 v6, s42, v30
	s_add_i32 s46, s18, 28
	v_lshl_add_u64 v[34:35], v[28:29], 0, v[74:75]
	global_load_dword v94, v[36:37], off nt
	global_load_dword v95, v[34:35], off nt
	v_lshlrev_b64 v[36:37], 12, v[6:7]
	v_or_b32_e32 v6, s44, v30
	v_lshl_add_u64 v[34:35], v[28:29], 0, v[38:39]
	v_lshlrev_b64 v[38:39], 12, v[6:7]
	v_or_b32_e32 v6, s46, v30
	v_lshlrev_b64 v[40:41], 12, v[6:7]
	v_lshl_add_u64 v[40:41], v[28:29], 0, v[40:41]
	v_lshl_add_u64 v[36:37], v[28:29], 0, v[36:37]
	v_lshl_add_u64 v[38:39], v[28:29], 0, v[38:39]
	global_load_dword v6, v[40:41], off nt
	global_load_dword v96, v[38:39], off nt
	global_load_dword v97, v[36:37], off nt
	global_load_dword v98, v[34:35], off nt
	v_or_b32_e32 v36, s17, v1
	v_or_b32_e32 v34, s18, v2
	s_add_i32 s16, s16, 16
	s_add_i32 s15, s15, 16
	s_add_i32 s14, s14, -16
	v_mad_u64_u32 v[34:35], s[18:19], v34, s25, v[4:5]
	v_mad_u64_u32 v[36:37], s[18:19], v36, s25, v[4:5]
	v_or_b32_e32 v35, s20, v1
	v_or_b32_e32 v37, s21, v2
	v_or_b32_e32 v44, s22, v1
	v_or_b32_e32 v42, s23, v2
	v_or_b32_e32 v68, s26, v1
	v_or_b32_e32 v66, s27, v2
	v_or_b32_e32 v72, s39, v1
	v_or_b32_e32 v70, s40, v2
	v_or_b32_e32 v76, s41, v1
	v_or_b32_e32 v74, s42, v2
	v_or_b32_e32 v80, s43, v1
	v_or_b32_e32 v78, s44, v2
	v_or_b32_e32 v84, s45, v1
	v_or_b32_e32 v82, s46, v2
	s_cmp_lg_u32 s14, 0
	v_mad_u64_u32 v[38:39], s[18:19], v37, s25, v[4:5]
	v_mad_u64_u32 v[40:41], s[18:19], v35, s25, v[4:5]
	v_mad_u64_u32 v[42:43], s[18:19], v42, s25, v[4:5]
	v_mad_u64_u32 v[44:45], s[18:19], v44, s25, v[4:5]
	v_mad_u64_u32 v[66:67], s[18:19], v66, s25, v[4:5]
	v_mad_u64_u32 v[68:69], s[18:19], v68, s25, v[4:5]
	v_mad_u64_u32 v[70:71], s[18:19], v70, s25, v[4:5]
	v_mad_u64_u32 v[72:73], s[18:19], v72, s25, v[4:5]
	v_mad_u64_u32 v[74:75], s[18:19], v74, s25, v[4:5]
	v_mad_u64_u32 v[76:77], s[18:19], v76, s25, v[4:5]
	v_mad_u64_u32 v[78:79], s[18:19], v78, s25, v[4:5]
	v_mad_u64_u32 v[80:81], s[18:19], v80, s25, v[4:5]
	v_mad_u64_u32 v[82:83], s[18:19], v82, s25, v[4:5]
	v_mad_u64_u32 v[84:85], s[18:19], v84, s25, v[4:5]
	s_waitcnt vmcnt(15)
	ds_write_b32 v34, v33
	s_waitcnt vmcnt(14)
	ds_write_b32 v36, v65
	s_waitcnt vmcnt(13)
	ds_write_b32 v38, v86
	s_waitcnt vmcnt(12)
	ds_write_b32 v40, v87
	s_waitcnt vmcnt(4)
	ds_write_b32 v42, v95
	ds_write_b32 v44, v88
	ds_write_b32 v66, v94
	ds_write_b32 v68, v89
	s_waitcnt vmcnt(0)
	ds_write_b32 v70, v98
	ds_write_b32 v72, v90
	ds_write_b32 v74, v97
	ds_write_b32 v76, v91
	ds_write_b32 v78, v96
	ds_write_b32 v80, v92
	ds_write_b32 v82, v6
	ds_write_b32 v84, v93
	s_cbranch_scc1 .LBB0_123
	s_waitcnt lgkmcnt(0)
	ds_read2_b32 v[28:29], v48 offset1:33
	v_and_b32_e32 v3, 0x1e0, v32
	v_lshlrev_b32_e32 v6, 1, v31
	s_waitcnt lgkmcnt(0)
	v_cvt_pk_bf16_f32 v28, v28, v29
	ds_read2_b32 v[34:35], v48 offset0:66 offset1:99
	v_lshl_add_u64 v[32:33], v[22:23], 0, v[6:7]
	v_or_b32_e32 v6, v3, v47
	s_waitcnt lgkmcnt(0)
	v_cvt_pk_bf16_f32 v29, v34, v35
	ds_read2_b32 v[34:35], v48 offset0:132 offset1:165
	v_lshlrev_b32_e32 v6, 9, v6
	s_waitcnt lgkmcnt(0)
	v_cvt_pk_bf16_f32 v30, v34, v35
	ds_read2_b32 v[34:35], v48 offset0:198 offset1:231
	s_waitcnt lgkmcnt(0)
	v_cvt_pk_bf16_f32 v31, v34, v35
	v_lshl_add_u64 v[36:37], v[32:33], 0, v[6:7]
	ds_read2_b32 v[34:35], v48 offset0:8 offset1:41
	global_store_dwordx4 v[36:37], v[28:31], off nt
	v_or_b32_e32 v6, v3, v49
	v_lshlrev_b32_e32 v6, 9, v6
	s_waitcnt lgkmcnt(0)
	v_cvt_pk_bf16_f32 v28, v34, v35
	ds_read2_b32 v[30:31], v48 offset0:74 offset1:107
	s_waitcnt lgkmcnt(0)
	v_cvt_pk_bf16_f32 v29, v30, v31
	ds_read2_b32 v[30:31], v48 offset0:140 offset1:173
	s_waitcnt lgkmcnt(0)
	v_cvt_pk_bf16_f32 v30, v30, v31
	ds_read2_b32 v[34:35], v48 offset0:206 offset1:239
	s_waitcnt lgkmcnt(0)
	v_cvt_pk_bf16_f32 v31, v34, v35
	v_lshl_add_u64 v[36:37], v[32:33], 0, v[6:7]
	ds_read2_b32 v[34:35], v48 offset0:16 offset1:49
	global_store_dwordx4 v[36:37], v[28:31], off nt
	v_or_b32_e32 v6, v3, v50
	v_lshlrev_b32_e32 v6, 9, v6
	s_waitcnt lgkmcnt(0)
	v_cvt_pk_bf16_f32 v28, v34, v35
	ds_read2_b32 v[30:31], v48 offset0:82 offset1:115
	s_waitcnt lgkmcnt(0)
	v_cvt_pk_bf16_f32 v29, v30, v31
	ds_read2_b32 v[30:31], v48 offset0:148 offset1:181
	s_waitcnt lgkmcnt(0)
	v_cvt_pk_bf16_f32 v30, v30, v31
	ds_read2_b32 v[34:35], v48 offset0:214 offset1:247
	s_waitcnt lgkmcnt(0)
	v_cvt_pk_bf16_f32 v31, v34, v35
	v_lshl_add_u64 v[36:37], v[32:33], 0, v[6:7]
	v_or_b32_e32 v3, v3, v51
	ds_read2_b32 v[34:35], v48 offset0:24 offset1:57
	global_store_dwordx4 v[36:37], v[28:31], off nt
	v_lshlrev_b32_e32 v6, 9, v3
	v_lshl_add_u64 v[32:33], v[32:33], 0, v[6:7]
	s_waitcnt lgkmcnt(0)
	v_cvt_pk_bf16_f32 v28, v34, v35
	ds_read2_b32 v[30:31], v48 offset0:90 offset1:123
	s_waitcnt lgkmcnt(0)
	v_cvt_pk_bf16_f32 v29, v30, v31
	ds_read2_b32 v[30:31], v48 offset0:156 offset1:189
	s_waitcnt lgkmcnt(0)
	v_cvt_pk_bf16_f32 v30, v30, v31
	ds_read2_b32 v[34:35], v48 offset0:222 offset1:255
	s_waitcnt lgkmcnt(0)
	v_cvt_pk_bf16_f32 v31, v34, v35
	global_store_dwordx4 v[32:33], v[28:31], off nt
	s_waitcnt lgkmcnt(0)

.LBB0_128:
	s_lshl_b32 s15, s12, 1
	s_lshl_b32 s18, s13, 1
	v_or_b32_e32 v32, s18, v6
	s_add_i32 s19, s15, 4
	s_add_i32 s20, s18, 4
	s_add_i32 s21, s15, 8
	s_add_i32 s22, s18, 8
	s_add_i32 s23, s15, 12
	s_add_i32 s26, s18, 12
	s_add_i32 s27, s15, 16
	s_add_i32 s39, s18, 16
	s_add_i32 s40, s15, 20
	s_add_i32 s41, s18, 20
	s_add_i32 s42, s15, 24
	s_add_i32 s43, s18, 24
	s_add_i32 s44, s15, 28
	s_add_i32 s45, s18, 28
	v_or_b32_e32 v34, s15, v3
	v_mad_u64_u32 v[32:33], s[16:17], v32, s37, v[28:29]
	v_or_b32_e32 v38, s19, v3
	v_or_b32_e32 v36, s20, v6
	v_or_b32_e32 v42, s21, v3
	v_or_b32_e32 v40, s22, v6
	v_or_b32_e32 v65, s23, v3
	v_or_b32_e32 v44, s26, v6
	v_or_b32_e32 v70, s27, v3
	v_or_b32_e32 v68, s39, v6
	v_or_b32_e32 v74, s40, v3
	v_or_b32_e32 v72, s41, v6
	v_or_b32_e32 v78, s42, v3
	v_or_b32_e32 v76, s43, v6
	v_or_b32_e32 v82, s44, v3
	v_or_b32_e32 v80, s45, v6
	v_mad_u64_u32 v[34:35], s[16:17], v34, s37, v[28:29]
	v_mad_u64_u32 v[36:37], s[16:17], v36, s37, v[28:29]
	v_mad_u64_u32 v[38:39], s[16:17], v38, s37, v[28:29]
	v_mad_u64_u32 v[40:41], s[16:17], v40, s37, v[28:29]
	v_mad_u64_u32 v[42:43], s[16:17], v42, s37, v[28:29]
	v_mad_u64_u32 v[44:45], s[16:17], v44, s37, v[28:29]
	v_mad_u64_u32 v[66:67], s[16:17], v65, s37, v[28:29]
	v_mad_u64_u32 v[68:69], s[16:17], v68, s37, v[28:29]
	v_mad_u64_u32 v[70:71], s[16:17], v70, s37, v[28:29]
	v_mad_u64_u32 v[72:73], s[16:17], v72, s37, v[28:29]
	v_mad_u64_u32 v[74:75], s[16:17], v74, s37, v[28:29]
	v_mad_u64_u32 v[76:77], s[16:17], v76, s37, v[28:29]
	v_mad_u64_u32 v[78:79], s[16:17], v78, s37, v[28:29]
	v_mad_u64_u32 v[80:81], s[16:17], v80, s37, v[28:29]
	v_mad_u64_u32 v[82:83], s[16:17], v82, s37, v[28:29]
	global_load_dword v65, v[32:33], off nt
	global_load_dword v84, v[34:35], off nt
	global_load_dword v85, v[36:37], off nt
	global_load_dword v86, v[38:39], off nt
	global_load_dword v87, v[40:41], off nt
	global_load_dword v88, v[42:43], off nt
	global_load_dword v89, v[44:45], off nt
	global_load_dword v90, v[66:67], off nt
	global_load_dword v91, v[68:69], off nt
	global_load_dword v92, v[70:71], off nt
	global_load_dword v93, v[72:73], off nt
	global_load_dword v94, v[74:75], off nt
	global_load_dword v95, v[76:77], off nt
	global_load_dword v96, v[78:79], off nt
	global_load_dword v97, v[80:81], off nt
	global_load_dword v98, v[82:83], off nt
	v_or_b32_e32 v34, s15, v1
	v_or_b32_e32 v32, s18, v2
	s_add_i32 s13, s13, 16
	s_add_i32 s12, s12, 16
	s_add_i32 s14, s14, -16
	v_mad_u64_u32 v[32:33], s[16:17], v32, s25, v[4:5]
	v_mad_u64_u32 v[34:35], s[16:17], v34, s25, v[4:5]
	v_or_b32_e32 v33, s19, v1
	v_or_b32_e32 v35, s20, v2
	v_or_b32_e32 v42, s21, v1
	v_or_b32_e32 v40, s22, v2
	v_or_b32_e32 v66, s23, v1
	v_or_b32_e32 v44, s26, v2
	v_or_b32_e32 v70, s27, v1
	v_or_b32_e32 v68, s39, v2
	v_or_b32_e32 v74, s40, v1
	v_or_b32_e32 v72, s41, v2
	v_or_b32_e32 v78, s42, v1
	v_or_b32_e32 v76, s43, v2
	v_or_b32_e32 v82, s44, v1
	v_or_b32_e32 v80, s45, v2
	s_cmp_lg_u32 s14, 0
	v_mad_u64_u32 v[36:37], s[16:17], v35, s25, v[4:5]
	v_mad_u64_u32 v[38:39], s[16:17], v33, s25, v[4:5]
	v_mad_u64_u32 v[40:41], s[16:17], v40, s25, v[4:5]
	v_mad_u64_u32 v[42:43], s[16:17], v42, s25, v[4:5]
	v_mad_u64_u32 v[44:45], s[16:17], v44, s25, v[4:5]
	v_mad_u64_u32 v[66:67], s[16:17], v66, s25, v[4:5]
	v_mad_u64_u32 v[68:69], s[16:17], v68, s25, v[4:5]
	v_mad_u64_u32 v[70:71], s[16:17], v70, s25, v[4:5]
	v_mad_u64_u32 v[72:73], s[16:17], v72, s25, v[4:5]
	v_mad_u64_u32 v[74:75], s[16:17], v74, s25, v[4:5]
	v_mad_u64_u32 v[76:77], s[16:17], v76, s25, v[4:5]
	v_mad_u64_u32 v[78:79], s[16:17], v78, s25, v[4:5]
	v_mad_u64_u32 v[80:81], s[16:17], v80, s25, v[4:5]
	v_mad_u64_u32 v[82:83], s[16:17], v82, s25, v[4:5]
	s_waitcnt vmcnt(15)
	ds_write_b32 v32, v65
	s_waitcnt vmcnt(14)
	ds_write_b32 v34, v84
	s_waitcnt vmcnt(13)
	ds_write_b32 v36, v85
	s_waitcnt vmcnt(12)
	ds_write_b32 v38, v86
	s_waitcnt vmcnt(11)
	ds_write_b32 v40, v87
	s_waitcnt vmcnt(10)
	ds_write_b32 v42, v88
	s_waitcnt vmcnt(9)
	ds_write_b32 v44, v89
	s_waitcnt vmcnt(8)
	ds_write_b32 v66, v90
	s_waitcnt vmcnt(7)
	ds_write_b32 v68, v91
	s_waitcnt vmcnt(6)
	ds_write_b32 v70, v92
	s_waitcnt vmcnt(5)
	ds_write_b32 v72, v93
	s_waitcnt vmcnt(4)
	ds_write_b32 v74, v94
	s_waitcnt vmcnt(3)
	ds_write_b32 v76, v95
	s_waitcnt vmcnt(2)
	ds_write_b32 v78, v96
	s_waitcnt vmcnt(1)
	ds_write_b32 v80, v97
	s_waitcnt vmcnt(0)
	ds_write_b32 v82, v98
	s_cbranch_scc1 .LBB0_128
	s_waitcnt lgkmcnt(0)
	ds_read2_b32 v[28:29], v48 offset1:33
	s_waitcnt lgkmcnt(0)
	v_cvt_pk_bf16_f32 v32, v28, v29
	ds_read2_b32 v[28:29], v48 offset0:66 offset1:99
	v_or_b32_e32 v3, v30, v47
	s_waitcnt lgkmcnt(0)
	v_cvt_pk_bf16_f32 v33, v28, v29
	ds_read2_b32 v[28:29], v48 offset0:132 offset1:165
	v_lshlrev_b32_e32 v6, 1, v31
	v_mul_u32_u24_e32 v3, 0x180, v3
	s_waitcnt lgkmcnt(0)
	v_cvt_pk_bf16_f32 v34, v28, v29
	ds_read2_b32 v[28:29], v48 offset0:198 offset1:231
	v_lshl_add_u64 v[36:37], v[24:25], 0, v[6:7]
	v_lshlrev_b32_e32 v6, 1, v3
	s_waitcnt lgkmcnt(0)
	v_cvt_pk_bf16_f32 v35, v28, v29
	ds_read2_b32 v[28:29], v48 offset0:8 offset1:41
	v_lshl_add_u64 v[38:39], v[36:37], 0, v[6:7]
	global_store_dwordx4 v[38:39], v[32:35], off nt
	v_or_b32_e32 v3, v30, v49
	v_mul_u32_u24_e32 v3, 0x180, v3
	s_waitcnt lgkmcnt(0)
	v_cvt_pk_bf16_f32 v32, v28, v29
	ds_read2_b32 v[28:29], v48 offset0:74 offset1:107
	s_waitcnt lgkmcnt(0)
	v_cvt_pk_bf16_f32 v33, v28, v29
	ds_read2_b32 v[28:29], v48 offset0:140 offset1:173
	s_waitcnt lgkmcnt(0)
	v_cvt_pk_bf16_f32 v34, v28, v29
	ds_read2_b32 v[28:29], v48 offset0:206 offset1:239
	v_lshlrev_b32_e32 v6, 1, v3
	s_waitcnt lgkmcnt(0)
	v_cvt_pk_bf16_f32 v35, v28, v29
	ds_read2_b32 v[28:29], v48 offset0:16 offset1:49
	v_lshl_add_u64 v[38:39], v[36:37], 0, v[6:7]
	global_store_dwordx4 v[38:39], v[32:35], off nt
	v_or_b32_e32 v3, v30, v50
	v_mul_u32_u24_e32 v3, 0x180, v3
	s_waitcnt lgkmcnt(0)
	v_cvt_pk_bf16_f32 v32, v28, v29
	ds_read2_b32 v[28:29], v48 offset0:82 offset1:115
	s_waitcnt lgkmcnt(0)
	v_cvt_pk_bf16_f32 v33, v28, v29
	ds_read2_b32 v[28:29], v48 offset0:148 offset1:181
	s_waitcnt lgkmcnt(0)
	v_cvt_pk_bf16_f32 v34, v28, v29
	ds_read2_b32 v[28:29], v48 offset0:214 offset1:247
	v_lshlrev_b32_e32 v6, 1, v3
	s_waitcnt lgkmcnt(0)
	v_cvt_pk_bf16_f32 v35, v28, v29
	ds_read2_b32 v[28:29], v48 offset0:24 offset1:57
	v_lshl_add_u64 v[38:39], v[36:37], 0, v[6:7]
	global_store_dwordx4 v[38:39], v[32:35], off nt
	v_or_b32_e32 v3, v30, v51
	v_mul_u32_u24_e32 v3, 0x180, v3
	s_waitcnt lgkmcnt(0)
	v_cvt_pk_bf16_f32 v32, v28, v29
	ds_read2_b32 v[28:29], v48 offset0:90 offset1:123
	s_waitcnt lgkmcnt(0)
	v_cvt_pk_bf16_f32 v33, v28, v29
	ds_read2_b32 v[28:29], v48 offset0:156 offset1:189
	s_waitcnt lgkmcnt(0)
	v_cvt_pk_bf16_f32 v34, v28, v29
	ds_read2_b32 v[28:29], v48 offset0:222 offset1:255
	v_lshlrev_b32_e32 v6, 1, v3
	s_waitcnt lgkmcnt(0)
	v_cvt_pk_bf16_f32 v35, v28, v29
	v_lshl_add_u64 v[28:29], v[36:37], 0, v[6:7]
	global_store_dwordx4 v[28:29], v[32:35], off nt
	s_waitcnt lgkmcnt(0)
